# GLU-type GEMM epilogues: v_pk_mul + moves split into plain multiplies with the moves folded in
# baseline (speedup 1.0000x reference)
; __device__ __forceinline__ float fast_sigmoid(float x) { return __builtin_amdgcn_rcpf(1.0f + __expf(-x)); }
; __device__ __forceinline__ void rows_rstd(const float* ssq, int row0, int fq, float (&rs)[2][4]) {
;     f32x4 pr[2][4];
; #pragma unroll
;     for (int ai = 0; ai < 2; ++ai)
; #pragma unroll
;         for (int m = 0; m < 4; ++m) pr[ai][m] = *(const f32x4*)(ssq + (size_t)(row0 + ai * HALF + m * 16) * 16 + 4 * fq);
; #pragma unroll
;     for (int ai = 0; ai < 2; ++ai)
; #pragma unroll
;         for (int m = 0; m < 4; ++m) { float t = (pr[ai][m][0] + pr[ai][m][1]) + (pr[ai][m][2] + pr[ai][m][3]); t += __shfl_xor(t, 16); t += __shfl_xor(t, 32); rs[ai][m] = __builtin_amdgcn_rsqf(t * (1.0f / 1024.0f) + 1e-6f); }
;     __device__ __forceinline__ void operator()(const f32x4 (&acc)[2][2][4][2], const Unit& u, int wr, int wc, int fr, int fq) const {
;     ...
;                 const int row = u.pm * BM + ai * HALF + wr * 64 + m * 16 + fr;
;                 const float rs = rsv[ai][m];
;                 float h[8];
; #pragma unroll
;                 for (int n = 0; n < 2; ++n)
; #pragma unroll
;                     for (int i = 0; i < 4; ++i) { const float g = acc[ai][0][m][n][i] * rs, up = acc[ai][1][m][n][i] * rs; h[4 * n + i] = g * up * fast_sigmoid(g); }
.LBB0_485:
	v_mbcnt_lo_u32_b32 v252, -1, 0
	v_mbcnt_hi_u32_b32 v252, -1, v252
	v_and_b32_e32 v252, 48, v252
	v_lshl_add_u32 v252, v149, 6, v252
	v_add_u32_e32 v252, 0x20000, v252
	v_lshl_add_u32 v170, s40, 8, v149
	v_ashrrev_i32_e32 v171, 31, v170
	v_or_b32_e32 v166, 16, v170
	v_lshlrev_b64 v[144:145], 6, v[170:171]
	v_ashrrev_i32_e32 v167, 31, v166
	v_or_b32_e32 v162, 32, v170
	v_lshl_add_u64 v[144:145], v[136:137], 0, v[144:145]
	v_lshlrev_b64 v[146:147], 6, v[166:167]
	v_ashrrev_i32_e32 v163, 31, v162
	v_or_b32_e32 v158, 48, v170
	v_lshl_add_u64 v[146:147], v[136:137], 0, v[146:147]
	ds_read_b128 v[178:181], v252 offset:0
	ds_read_b128 v[182:185], v252 offset:1024
	v_lshlrev_b64 v[144:145], 6, v[162:163]
	v_ashrrev_i32_e32 v159, 31, v158
	v_add_u32_e32 v154, 0x80, v170
	v_lshl_add_u64 v[144:145], v[136:137], 0, v[144:145]
	v_lshlrev_b64 v[146:147], 6, v[158:159]
	v_ashrrev_i32_e32 v155, 31, v154
	v_lshl_add_u64 v[146:147], v[136:137], 0, v[146:147]
	ds_read_b128 v[186:189], v252 offset:2048
	ds_read_b128 v[190:193], v252 offset:3072
	v_lshlrev_b64 v[144:145], 6, v[154:155]
	v_lshl_add_u64 v[144:145], v[136:137], 0, v[144:145]
	ds_read_b128 v[194:197], v252 offset:8192
	v_add_u32_e32 v150, 0x90, v170
	v_ashrrev_i32_e32 v151, 31, v150
	v_lshlrev_b64 v[144:145], 6, v[150:151]
	v_add_u32_e32 v146, 0xa0, v170
	v_lshl_add_u64 v[144:145], v[136:137], 0, v[144:145]
	v_ashrrev_i32_e32 v147, 31, v146
	ds_read_b128 v[198:201], v252 offset:9216
	v_lshlrev_b64 v[144:145], 6, v[146:147]
	v_lshl_add_u64 v[144:145], v[136:137], 0, v[144:145]
	ds_read_b128 v[202:205], v252 offset:10240
	v_add_u32_e32 v144, 0xb0, v170
	v_ashrrev_i32_e32 v145, 31, v144
	v_lshlrev_b64 v[206:207], 6, v[144:145]
	v_lshl_add_u64 v[206:207], v[136:137], 0, v[206:207]
	ds_read_b128 v[206:209], v252 offset:11264
	v_and_b32_e32 v147, 64, v175
	v_xor_b32_e32 v145, 16, v175
	v_add_u32_e32 v147, 64, v147
	v_xor_b32_e32 v148, 32, v175
	v_cmp_lt_i32_e32 vcc, v145, v147
	v_lshl_or_b32 v172, s54, 7, v157
	v_ashrrev_i32_e32 v173, 31, v172
	v_cndmask_b32_e32 v145, v175, v145, vcc
	v_cmp_lt_i32_e32 vcc, v148, v147
	v_lshlrev_b32_e32 v145, 2, v145
	s_waitcnt lgkmcnt(0)
	v_mov_b32_e32 v210, v179
	v_mov_b32_e32 v211, v180
	v_mov_b32_e32 v179, v181
	v_pk_add_f32 v[178:179], v[210:211], v[178:179]
	v_mov_b32_e32 v180, v183
	v_mov_b32_e32 v181, v184
	v_mov_b32_e32 v183, v185
	v_cndmask_b32_e32 v147, v175, v148, vcc
	v_mov_b32_e32 v184, v187
	v_mov_b32_e32 v185, v188
	v_mov_b32_e32 v187, v189
	v_mov_b32_e32 v188, v191
	v_mov_b32_e32 v189, v192
	v_mov_b32_e32 v191, v193
	v_add_f32_e32 v148, v178, v179
	v_pk_add_f32 v[178:179], v[180:181], v[182:183]
	v_pk_add_f32 v[180:181], v[184:185], v[186:187]
	v_pk_add_f32 v[182:183], v[188:189], v[190:191]
	v_mov_b32_e32 v192, v195
	v_mov_b32_e32 v193, v196
	v_mov_b32_e32 v195, v197
	ds_bpermute_b32 v151, v145, v148
	v_add_f32_e32 v152, v178, v179
	v_add_f32_e32 v155, v180, v181
	v_add_f32_e32 v156, v182, v183
	v_pk_add_f32 v[184:185], v[192:193], v[194:195]
	ds_bpermute_b32 v160, v145, v152
	ds_bpermute_b32 v163, v145, v155
	ds_bpermute_b32 v164, v145, v156
	v_add_f32_e32 v159, v184, v185
	ds_bpermute_b32 v167, v145, v159
	v_lshlrev_b32_e32 v147, 2, v147
	s_waitcnt lgkmcnt(4)
	v_add_f32_e32 v148, v148, v151
	ds_bpermute_b32 v151, v147, v148
	s_waitcnt lgkmcnt(4)
	v_add_f32_e32 v152, v152, v160
	s_waitcnt lgkmcnt(3)
	v_add_f32_e32 v155, v155, v163
	s_waitcnt lgkmcnt(2)
	v_add_f32_e32 v156, v156, v164
	ds_bpermute_b32 v160, v147, v152
	ds_bpermute_b32 v163, v147, v155
	ds_bpermute_b32 v164, v147, v156
	s_waitcnt lgkmcnt(4)
	v_add_f32_e32 v159, v159, v167
	ds_bpermute_b32 v167, v147, v159
	s_waitcnt lgkmcnt(4)
	v_add_f32_e32 v148, v148, v151
	v_fmamk_f32 v148, v148, 0x3a800000, v176
	s_waitcnt lgkmcnt(3)
	v_add_f32_e32 v151, v152, v160
	s_waitcnt lgkmcnt(2)
	v_add_f32_e32 v152, v155, v163
	s_waitcnt lgkmcnt(1)
	v_add_f32_e32 v155, v156, v164
	v_mov_b32_e32 v180, v199
	v_mov_b32_e32 v181, v200
	v_mov_b32_e32 v199, v201
	v_rsq_f32_e32 v178, v148
	v_fmamk_f32 v148, v151, 0x3a800000, v176
	v_fmamk_f32 v151, v152, 0x3a800000, v176
	v_fmamk_f32 v152, v155, 0x3a800000, v176
	v_pk_add_f32 v[180:181], v[180:181], v[198:199]
	v_rsq_f32_e32 v174, v148
	v_add_f32_e32 v148, v180, v181
	v_rsq_f32_e32 v164, v152
	s_waitcnt lgkmcnt(0)
	v_add_f32_e32 v152, v159, v167
	v_mov_b32_e32 v180, v203
	v_mov_b32_e32 v181, v204
	v_mov_b32_e32 v203, v205
	v_fmamk_f32 v152, v152, 0x3a800000, v176
	v_pk_add_f32 v[180:181], v[180:181], v[202:203]
	v_rsq_f32_e32 v160, v152
	v_add_f32_e32 v152, v180, v181
	v_mov_b32_e32 v180, v207
	v_mov_b32_e32 v181, v208
	v_mov_b32_e32 v207, v209
	v_pk_add_f32 v[180:181], v[180:181], v[206:207]
	v_rsq_f32_e32 v168, v151
	v_add_f32_e32 v156, v180, v181
	v_mul_f32_e32 v180, v124, v178
	v_mul_f32_e32 v181, v120, v178
	ds_bpermute_b32 v151, v145, v148
	v_mul_f32_e32 v120, 0xbfb8aa3b, v180
	v_exp_f32_e32 v124, v120
	v_mul_f32_e32 v120, v125, v178
	v_mul_f32_e32 v121, v121, v178
	s_waitcnt lgkmcnt(0)
	v_add_f32_e32 v148, v148, v151
	v_mul_f32_e32 v125, 0xbfb8aa3b, v120
	v_exp_f32_e32 v125, v125
	ds_bpermute_b32 v151, v147, v148
	ds_bpermute_b32 v155, v145, v152
	ds_bpermute_b32 v145, v145, v156
	v_add_f32_e32 v125, 1.0, v125
	v_rcp_f32_e32 v125, v125
	v_mul_f32_e32 v120, v120, v121
	s_waitcnt lgkmcnt(2)
	v_add_f32_e32 v148, v148, v151
	s_waitcnt lgkmcnt(1)
	v_add_f32_e32 v151, v152, v155
	s_waitcnt lgkmcnt(0)
; __device__ __forceinline__ unsigned cvt_pk_bf16(float lo, float hi) { unsigned r; asm volatile("v_cvt_pk_bf16_f32 %0, %1, %2" : "=v"(r) : "v"(lo), "v"(hi)); return r; }
; __device__ __forceinline__ float fast_sigmoid(float x) { return __builtin_amdgcn_rcpf(1.0f + __expf(-x)); }
;     __device__ __forceinline__ void operator()(const f32x4 (&acc)[2][2][4][2], const Unit& u, int wr, int wc, int fr, int fq) const {
;     ...
;         for (int ai = 0; ai < 2; ++ai)
; #pragma unroll
;             for (int m = 0; m < 4; ++m) {
;                 const int row = u.pm * BM + ai * HALF + wr * 64 + m * 16 + fr;
;                 const float rs = rsv[ai][m];
;                 float h[8];
; #pragma unroll
;                 for (int n = 0; n < 2; ++n)
; #pragma unroll
;                     for (int i = 0; i < 4; ++i) { const float g = acc[ai][0][m][n][i] * rs, up = acc[ai][1][m][n][i] * rs; h[4 * n + i] = g * up * fast_sigmoid(g); }
;                 u32x4 w; w.x = cvt_pk_bf16(h[0], h[1]); w.y = cvt_pk_bf16(h[2], h[3]); w.z = cvt_pk_bf16(h[4], h[5]); w.w = cvt_pk_bf16(h[6], h[7]);
;                 *(u32x4*)(H + (size_t)row * 2816 + col0) = w;
	v_add_f32_e32 v145, v156, v145
	v_mul_f32_e32 v125, v120, v125
	ds_bpermute_b32 v152, v147, v151
	ds_bpermute_b32 v147, v147, v145
	v_mul_f32_e32 v120, v126, v178
	v_mul_f32_e32 v121, v122, v178
	v_add_f32_e32 v124, 1.0, v124
	v_mul_f32_e32 v122, 0xbfb8aa3b, v120
	v_exp_f32_e32 v126, v122
	v_mul_f32_e32 v122, v127, v178
	v_mul_f32_e32 v123, v123, v178
	v_fmamk_f32 v148, v148, 0x3a800000, v176
	v_rcp_f32_e32 v124, v124
	v_mul_f32_e32 v127, 0xbfb8aa3b, v122
	v_rsq_f32_e32 v156, v148
	s_waitcnt lgkmcnt(1)
	v_add_f32_e32 v148, v151, v152
	s_waitcnt lgkmcnt(0)
	v_add_f32_e32 v145, v145, v147
	v_exp_f32_e32 v127, v127
	v_fmamk_f32 v148, v148, 0x3a800000, v176
	v_fmamk_f32 v145, v145, 0x3a800000, v176
	v_rsq_f32_e32 v152, v148
	v_rsq_f32_e32 v148, v145
	v_mul_f32_e32 v145, v180, v181
	v_mul_f32_e32 v124, v145, v124
	v_mul_f32_e32 v145, v120, v121
	v_add_f32_e32 v120, 1.0, v126
	v_rcp_f32_e32 v126, v120
	v_add_f32_e32 v120, 1.0, v127
	v_rcp_f32_e32 v127, v120
	v_mul_f32_e32 v120, v116, v178
	v_mul_f32_e32 v121, v112, v178
	v_mul_f32_e32 v116, v122, v123
	v_mul_f32_e32 v112, 0xbfb8aa3b, v120
	v_exp_f32_e32 v112, v112
	v_mul_f32_e32 v122, v116, v127
	v_mul_f32_e32 v120, v120, v121
	v_mul_f32_e32 v126, v145, v126
	v_add_f32_e32 v112, 1.0, v112
	v_rcp_f32_e32 v116, v112
	v_mul_f32_e32 v112, v117, v178
	v_mul_f32_e32 v113, v113, v178
	v_mov_b32_e32 v123, v104
	v_mul_f32_e32 v117, 0xbfb8aa3b, v112
	v_exp_f32_e32 v117, v117
	v_mul_f32_e32 v120, v120, v116
	v_mul_f32_e32 v116, v112, v113
	v_add_f32_e32 v112, 1.0, v117
	v_rcp_f32_e32 v117, v112
	v_mul_f32_e32 v112, v118, v178
	v_mul_f32_e32 v113, v114, v178
	s_andn2_b64 vcc, exec, s[20:21]
	v_mul_f32_e32 v114, 0xbfb8aa3b, v112
	v_exp_f32_e32 v118, v114
	v_mul_f32_e32 v114, v119, v178
	v_mul_f32_e32 v115, v115, v178
	v_mul_f32_e32 v121, v116, v117
	v_mul_f32_e32 v119, 0xbfb8aa3b, v114
	v_exp_f32_e32 v119, v119
	v_add_f32_e32 v116, 1.0, v118
	v_rcp_f32_e32 v116, v116
	v_mul_f32_e32 v112, v112, v113
	v_add_f32_e32 v117, 1.0, v119
	v_rcp_f32_e32 v117, v117
	v_mul_f32_e32 v113, v114, v115
	v_mul_f32_e32 v112, v112, v116
	v_cvt_pk_bf16_f32 v116, v124, v125
	v_mul_f32_e32 v113, v113, v117
	v_cvt_pk_bf16_f32 v117, v126, v122
	v_mul_f32_e32 v122, v108, v174
	v_mul_f32_e32 v123, v123, v174
	v_cvt_pk_bf16_f32 v118, v120, v121
	v_cvt_pk_bf16_f32 v119, v112, v113
	v_mov_b64_e32 v[112:113], s[6:7]
	v_mul_f32_e32 v104, 0xbfb8aa3b, v122
	v_exp_f32_e32 v108, v104
	v_mul_f32_e32 v104, v109, v174
	v_mul_f32_e32 v105, v105, v174
	v_mad_i64_i32 v[120:121], s[42:43], v170, s53, v[112:113]
	v_mul_f32_e32 v109, 0xbfb8aa3b, v104
	v_exp_f32_e32 v109, v109
	v_mul_f32_e32 v104, v104, v105
	v_mov_b32_e32 v105, v106
	v_add_f32_e32 v108, 1.0, v108
	v_add_f32_e32 v109, 1.0, v109
	v_rcp_f32_e32 v109, v109
	v_rcp_f32_e32 v108, v108
	v_lshlrev_b64 v[114:115], 1, v[172:173]
	v_lshl_add_u64 v[120:121], v[120:121], 0, v[114:115]
	v_mul_f32_e32 v109, v104, v109
	v_mul_f32_e32 v104, v110, v174
	v_mul_f32_e32 v105, v105, v174
	global_store_dwordx4 v[120:121], v[116:119], off
	v_mul_f32_e32 v106, 0xbfb8aa3b, v104
	v_exp_f32_e32 v110, v106
	v_mul_f32_e32 v106, v111, v174
	v_mul_f32_e32 v107, v107, v174
	v_mul_f32_e32 v116, v122, v123
	v_mul_f32_e32 v111, 0xbfb8aa3b, v106
	v_exp_f32_e32 v111, v111
	v_mul_f32_e32 v108, v116, v108
	v_mul_f32_e32 v116, v104, v105
	v_add_f32_e32 v104, 1.0, v110
	v_rcp_f32_e32 v110, v104
	v_add_f32_e32 v104, 1.0, v111
	v_rcp_f32_e32 v111, v104
	v_mul_f32_e32 v104, v100, v174
	v_mul_f32_e32 v105, v96, v174
	v_mul_f32_e32 v106, v106, v107
	v_mul_f32_e32 v96, 0xbfb8aa3b, v104
	v_exp_f32_e32 v96, v96
	v_mul_f32_e32 v104, v104, v105
	v_mul_f32_e32 v100, v116, v110
	v_mul_f32_e32 v106, v106, v111
	v_add_f32_e32 v96, 1.0, v96
	v_rcp_f32_e32 v107, v96
	v_mul_f32_e32 v96, v101, v174
	v_mul_f32_e32 v97, v97, v174
	s_mov_b64 s[20:21], -1
	v_mul_f32_e32 v101, 0xbfb8aa3b, v96
	v_exp_f32_e32 v101, v101
	v_mul_f32_e32 v105, v96, v97
	v_mov_b32_e32 v97, v98
	v_mul_f32_e32 v104, v104, v107
	v_add_f32_e32 v96, 1.0, v101
	v_rcp_f32_e32 v101, v96
	v_mul_f32_e32 v96, v102, v174
	v_mul_f32_e32 v97, v97, v174
	v_mul_f32_e32 v101, v105, v101
	v_mul_f32_e32 v98, 0xbfb8aa3b, v96
	v_exp_f32_e32 v102, v98
	v_mul_f32_e32 v98, v103, v174
	v_mul_f32_e32 v99, v99, v174
	v_mul_f32_e32 v96, v96, v97
	v_mul_f32_e32 v103, 0xbfb8aa3b, v98
	v_exp_f32_e32 v103, v103
	v_add_f32_e32 v102, 1.0, v102
	v_rcp_f32_e32 v102, v102
	v_add_f32_e32 v103, 1.0, v103
	v_rcp_f32_e32 v103, v103
	v_mul_f32_e32 v102, v96, v102
	v_mul_f32_e32 v96, v98, v99
	v_mul_f32_e32 v99, v96, v103
	v_cvt_pk_bf16_f32 v96, v108, v109
	v_cvt_pk_bf16_f32 v97, v100, v106
	v_cvt_pk_bf16_f32 v98, v104, v101
	v_cvt_pk_bf16_f32 v99, v102, v99
	v_mul_f32_e32 v102, v92, v168
	v_mul_f32_e32 v103, v88, v168
	v_mad_i64_i32 v[100:101], s[42:43], v166, s53, v[112:113]
	v_mul_f32_e32 v88, 0xbfb8aa3b, v102
	v_exp_f32_e32 v92, v88
	v_mul_f32_e32 v88, v93, v168
	v_mul_f32_e32 v89, v89, v168
	v_lshl_add_u64 v[100:101], v[100:101], 0, v[114:115]
	v_mul_f32_e32 v93, 0xbfb8aa3b, v88
	v_exp_f32_e32 v93, v93
	v_mul_f32_e32 v88, v88, v89
	v_mov_b32_e32 v89, v90
	v_add_f32_e32 v92, 1.0, v92
	v_add_f32_e32 v93, 1.0, v93
	v_rcp_f32_e32 v93, v93
	v_rcp_f32_e32 v92, v92
	global_store_dwordx4 v[100:101], v[96:99], off
	v_mul_f32_e32 v93, v88, v93
	v_mul_f32_e32 v88, v94, v168
	v_mul_f32_e32 v89, v89, v168
	v_mul_f32_e32 v96, v102, v103
	v_mul_f32_e32 v90, 0xbfb8aa3b, v88
	v_exp_f32_e32 v94, v90
	v_mul_f32_e32 v90, v95, v168
	v_mul_f32_e32 v91, v91, v168
	v_mul_f32_e32 v92, v96, v92
	v_mul_f32_e32 v95, 0xbfb8aa3b, v90
	v_exp_f32_e32 v95, v95
	v_mul_f32_e32 v96, v88, v89
	v_add_f32_e32 v88, 1.0, v94
	v_rcp_f32_e32 v94, v88
; __device__ __forceinline__ unsigned cvt_pk_bf16(float lo, float hi) { unsigned r; asm volatile("v_cvt_pk_bf16_f32 %0, %1, %2" : "=v"(r) : "v"(lo), "v"(hi)); return r; }
; __device__ __forceinline__ float fast_sigmoid(float x) { return __builtin_amdgcn_rcpf(1.0f + __expf(-x)); }
;     __device__ __forceinline__ void operator()(const f32x4 (&acc)[2][2][4][2], const Unit& u, int wr, int wc, int fr, int fq) const {
;     ...
;         for (int ai = 0; ai < 2; ++ai)
; #pragma unroll
;             for (int m = 0; m < 4; ++m) {
;                 const int row = u.pm * BM + ai * HALF + wr * 64 + m * 16 + fr;
;                 const float rs = rsv[ai][m];
;                 float h[8];
; #pragma unroll
;                 for (int n = 0; n < 2; ++n)
; #pragma unroll
;                     for (int i = 0; i < 4; ++i) { const float g = acc[ai][0][m][n][i] * rs, up = acc[ai][1][m][n][i] * rs; h[4 * n + i] = g * up * fast_sigmoid(g); }
;                 u32x4 w; w.x = cvt_pk_bf16(h[0], h[1]); w.y = cvt_pk_bf16(h[2], h[3]); w.z = cvt_pk_bf16(h[4], h[5]); w.w = cvt_pk_bf16(h[6], h[7]);
;                 *(u32x4*)(H + (size_t)row * 2816 + col0) = w;
	v_add_f32_e32 v88, 1.0, v95
	v_rcp_f32_e32 v95, v88
	v_mul_f32_e32 v88, v84, v168
	v_mul_f32_e32 v89, v80, v168
	v_mul_f32_e32 v90, v90, v91
	v_mul_f32_e32 v80, 0xbfb8aa3b, v88
	v_exp_f32_e32 v80, v80
	v_mul_f32_e32 v88, v88, v89
	v_mul_f32_e32 v84, v96, v94
	v_mul_f32_e32 v90, v90, v95
	v_add_f32_e32 v80, 1.0, v80
	v_rcp_f32_e32 v91, v80
	v_mul_f32_e32 v80, v85, v168
	v_mul_f32_e32 v81, v81, v168
	v_mul_f32_e32 v88, v88, v91
	v_mul_f32_e32 v85, 0xbfb8aa3b, v80
	v_exp_f32_e32 v85, v85
	v_mul_f32_e32 v89, v80, v81
	v_add_f32_e32 v80, 1.0, v85
	v_rcp_f32_e32 v85, v80
	v_mul_f32_e32 v80, v86, v168
	v_mul_f32_e32 v81, v82, v168
	v_mul_f32_e32 v85, v89, v85
	v_mul_f32_e32 v82, 0xbfb8aa3b, v80
	v_exp_f32_e32 v86, v82
	v_mul_f32_e32 v82, v87, v168
	v_mul_f32_e32 v83, v83, v168
	v_mul_f32_e32 v80, v80, v81
	v_mul_f32_e32 v87, 0xbfb8aa3b, v82
	v_exp_f32_e32 v87, v87
	v_add_f32_e32 v86, 1.0, v86
	v_rcp_f32_e32 v86, v86
	v_add_f32_e32 v87, 1.0, v87
	v_rcp_f32_e32 v87, v87
	v_mul_f32_e32 v86, v80, v86
	v_mul_f32_e32 v80, v82, v83
	v_mul_f32_e32 v83, v80, v87
	v_cvt_pk_bf16_f32 v80, v92, v93
	v_cvt_pk_bf16_f32 v81, v84, v90
	v_cvt_pk_bf16_f32 v82, v88, v85
	v_cvt_pk_bf16_f32 v83, v86, v83
	v_mul_f32_e32 v86, v76, v164
	v_mul_f32_e32 v87, v72, v164
	v_mad_i64_i32 v[84:85], s[42:43], v162, s53, v[112:113]
	v_mul_f32_e32 v72, 0xbfb8aa3b, v86
	v_exp_f32_e32 v76, v72
	v_mul_f32_e32 v72, v77, v164
	v_mul_f32_e32 v73, v73, v164
	v_lshl_add_u64 v[84:85], v[84:85], 0, v[114:115]
	v_mul_f32_e32 v77, 0xbfb8aa3b, v72
	v_exp_f32_e32 v77, v77
	v_mul_f32_e32 v72, v72, v73
	v_mov_b32_e32 v73, v74
	v_add_f32_e32 v76, 1.0, v76
	v_add_f32_e32 v77, 1.0, v77
	v_rcp_f32_e32 v77, v77
	v_rcp_f32_e32 v76, v76
	global_store_dwordx4 v[84:85], v[80:83], off
	v_mul_f32_e32 v77, v72, v77
	v_mul_f32_e32 v72, v78, v164
	v_mul_f32_e32 v73, v73, v164
	v_mul_f32_e32 v80, v86, v87
	v_mul_f32_e32 v74, 0xbfb8aa3b, v72
	v_exp_f32_e32 v78, v74
	v_mul_f32_e32 v74, v79, v164
	v_mul_f32_e32 v75, v75, v164
	v_mul_f32_e32 v76, v80, v76
	v_mul_f32_e32 v79, 0xbfb8aa3b, v74
	v_exp_f32_e32 v79, v79
	v_mul_f32_e32 v80, v72, v73
	v_add_f32_e32 v72, 1.0, v78
	v_rcp_f32_e32 v78, v72
	v_add_f32_e32 v72, 1.0, v79
	v_rcp_f32_e32 v79, v72
	v_mul_f32_e32 v72, v68, v164
	v_mul_f32_e32 v73, v64, v164
	v_mul_f32_e32 v74, v74, v75
	v_mul_f32_e32 v64, 0xbfb8aa3b, v72
	v_exp_f32_e32 v64, v64
	v_mul_f32_e32 v72, v72, v73
	v_mul_f32_e32 v68, v80, v78
	v_mul_f32_e32 v74, v74, v79
	v_add_f32_e32 v64, 1.0, v64
	v_rcp_f32_e32 v75, v64
	v_mul_f32_e32 v64, v69, v164
	v_mul_f32_e32 v65, v65, v164
	v_mul_f32_e32 v72, v72, v75
	v_mul_f32_e32 v69, 0xbfb8aa3b, v64
	v_exp_f32_e32 v69, v69
	v_mul_f32_e32 v73, v64, v65
	v_add_f32_e32 v64, 1.0, v69
	v_rcp_f32_e32 v69, v64
	v_mul_f32_e32 v64, v70, v164
	v_mul_f32_e32 v65, v66, v164
	v_mul_f32_e32 v69, v73, v69
	v_mul_f32_e32 v66, 0xbfb8aa3b, v64
	v_exp_f32_e32 v70, v66
	v_mul_f32_e32 v66, v71, v164
	v_mul_f32_e32 v67, v67, v164
	v_mul_f32_e32 v64, v64, v65
	v_mul_f32_e32 v71, 0xbfb8aa3b, v66
	v_exp_f32_e32 v71, v71
	v_add_f32_e32 v70, 1.0, v70
	v_rcp_f32_e32 v70, v70
	v_add_f32_e32 v71, 1.0, v71
	v_rcp_f32_e32 v71, v71
	v_mul_f32_e32 v70, v64, v70
	v_mul_f32_e32 v64, v66, v67
	v_mul_f32_e32 v67, v64, v71
	v_cvt_pk_bf16_f32 v64, v76, v77
	v_cvt_pk_bf16_f32 v65, v68, v74
	v_cvt_pk_bf16_f32 v66, v72, v69
	v_cvt_pk_bf16_f32 v67, v70, v67
	v_mul_f32_e32 v70, v60, v160
	v_mul_f32_e32 v71, v56, v160
	v_mad_i64_i32 v[68:69], s[42:43], v158, s53, v[112:113]
	v_mul_f32_e32 v56, 0xbfb8aa3b, v70
	v_exp_f32_e32 v60, v56
	v_mul_f32_e32 v56, v61, v160
	v_mul_f32_e32 v57, v57, v160
	v_lshl_add_u64 v[68:69], v[68:69], 0, v[114:115]
	v_mul_f32_e32 v61, 0xbfb8aa3b, v56
	v_exp_f32_e32 v61, v61
	v_mul_f32_e32 v56, v56, v57
	v_mov_b32_e32 v57, v58
	v_add_f32_e32 v60, 1.0, v60
	v_add_f32_e32 v61, 1.0, v61
	v_rcp_f32_e32 v61, v61
	v_rcp_f32_e32 v60, v60
	global_store_dwordx4 v[68:69], v[64:67], off
	v_mul_f32_e32 v61, v56, v61
	v_mul_f32_e32 v56, v62, v160
	v_mul_f32_e32 v57, v57, v160
	v_mul_f32_e32 v64, v70, v71
	v_mul_f32_e32 v58, 0xbfb8aa3b, v56
	v_exp_f32_e32 v62, v58
	v_mul_f32_e32 v58, v63, v160
	v_mul_f32_e32 v59, v59, v160
	v_mul_f32_e32 v60, v64, v60
	v_mul_f32_e32 v63, 0xbfb8aa3b, v58
	v_exp_f32_e32 v63, v63
	v_mul_f32_e32 v64, v56, v57
	v_add_f32_e32 v56, 1.0, v62
	v_rcp_f32_e32 v62, v56
	v_add_f32_e32 v56, 1.0, v63
	v_rcp_f32_e32 v63, v56
	v_mul_f32_e32 v56, v52, v160
	v_mul_f32_e32 v57, v48, v160
	v_mul_f32_e32 v58, v58, v59
	v_mul_f32_e32 v48, 0xbfb8aa3b, v56
	v_exp_f32_e32 v48, v48
	v_mul_f32_e32 v56, v56, v57
	v_mul_f32_e32 v52, v64, v62
	v_mul_f32_e32 v58, v58, v63
	v_add_f32_e32 v48, 1.0, v48
	v_rcp_f32_e32 v59, v48
	v_mul_f32_e32 v48, v53, v160
	v_mul_f32_e32 v49, v49, v160
	v_mul_f32_e32 v56, v56, v59
	v_mul_f32_e32 v53, 0xbfb8aa3b, v48
	v_exp_f32_e32 v53, v53
	v_mul_f32_e32 v57, v48, v49
	v_add_f32_e32 v48, 1.0, v53
	v_rcp_f32_e32 v53, v48
	v_mul_f32_e32 v48, v54, v160
	v_mul_f32_e32 v49, v50, v160
	v_mul_f32_e32 v53, v57, v53
	v_mul_f32_e32 v50, 0xbfb8aa3b, v48
	v_exp_f32_e32 v54, v50
	v_mul_f32_e32 v50, v55, v160
	v_mul_f32_e32 v51, v51, v160
	v_mul_f32_e32 v48, v48, v49
	v_mul_f32_e32 v55, 0xbfb8aa3b, v50
	v_exp_f32_e32 v55, v55
	v_add_f32_e32 v54, 1.0, v54
	v_rcp_f32_e32 v54, v54
	v_add_f32_e32 v55, 1.0, v55
	v_rcp_f32_e32 v55, v55
	v_mul_f32_e32 v54, v48, v54
	v_mul_f32_e32 v48, v50, v51
	v_mul_f32_e32 v51, v48, v55
	v_cvt_pk_bf16_f32 v48, v60, v61
	v_cvt_pk_bf16_f32 v49, v52, v58
	v_cvt_pk_bf16_f32 v50, v56, v53
	v_cvt_pk_bf16_f32 v51, v54, v51
	v_mul_f32_e32 v54, v44, v156
	v_mul_f32_e32 v55, v40, v156
	v_mad_i64_i32 v[52:53], s[42:43], v154, s53, v[112:113]
; __device__ __forceinline__ unsigned cvt_pk_bf16(float lo, float hi) { unsigned r; asm volatile("v_cvt_pk_bf16_f32 %0, %1, %2" : "=v"(r) : "v"(lo), "v"(hi)); return r; }
; __device__ __forceinline__ float fast_sigmoid(float x) { return __builtin_amdgcn_rcpf(1.0f + __expf(-x)); }
;     __device__ __forceinline__ void operator()(const f32x4 (&acc)[2][2][4][2], const Unit& u, int wr, int wc, int fr, int fq) const {
;     ...
;         for (int ai = 0; ai < 2; ++ai)
; #pragma unroll
;             for (int m = 0; m < 4; ++m) {
;                 const int row = u.pm * BM + ai * HALF + wr * 64 + m * 16 + fr;
;                 const float rs = rsv[ai][m];
;                 float h[8];
; #pragma unroll
;                 for (int n = 0; n < 2; ++n)
; #pragma unroll
;                     for (int i = 0; i < 4; ++i) { const float g = acc[ai][0][m][n][i] * rs, up = acc[ai][1][m][n][i] * rs; h[4 * n + i] = g * up * fast_sigmoid(g); }
;                 u32x4 w; w.x = cvt_pk_bf16(h[0], h[1]); w.y = cvt_pk_bf16(h[2], h[3]); w.z = cvt_pk_bf16(h[4], h[5]); w.w = cvt_pk_bf16(h[6], h[7]);
;                 *(u32x4*)(H + (size_t)row * 2816 + col0) = w;
	v_mul_f32_e32 v40, 0xbfb8aa3b, v54
	v_exp_f32_e32 v44, v40
	v_mul_f32_e32 v40, v45, v156
	v_mul_f32_e32 v41, v41, v156
	v_lshl_add_u64 v[52:53], v[52:53], 0, v[114:115]
	v_mul_f32_e32 v45, 0xbfb8aa3b, v40
	v_exp_f32_e32 v45, v45
	v_mul_f32_e32 v40, v40, v41
	v_mov_b32_e32 v41, v42
	v_add_f32_e32 v44, 1.0, v44
	v_add_f32_e32 v45, 1.0, v45
	v_rcp_f32_e32 v45, v45
	v_rcp_f32_e32 v44, v44
	global_store_dwordx4 v[52:53], v[48:51], off
	v_mul_f32_e32 v45, v40, v45
	v_mul_f32_e32 v40, v46, v156
	v_mul_f32_e32 v41, v41, v156
	v_mul_f32_e32 v48, v54, v55
	v_mul_f32_e32 v42, 0xbfb8aa3b, v40
	v_exp_f32_e32 v46, v42
	v_mul_f32_e32 v42, v47, v156
	v_mul_f32_e32 v43, v43, v156
	v_mul_f32_e32 v44, v48, v44
	v_mul_f32_e32 v47, 0xbfb8aa3b, v42
	v_exp_f32_e32 v47, v47
	v_mul_f32_e32 v48, v40, v41
	v_add_f32_e32 v40, 1.0, v46
	v_rcp_f32_e32 v46, v40
	v_add_f32_e32 v40, 1.0, v47
	v_rcp_f32_e32 v47, v40
	v_mul_f32_e32 v40, v36, v156
	v_mul_f32_e32 v41, v32, v156
	v_mul_f32_e32 v42, v42, v43
	v_mul_f32_e32 v32, 0xbfb8aa3b, v40
	v_exp_f32_e32 v32, v32
	v_mul_f32_e32 v40, v40, v41
	v_mul_f32_e32 v36, v48, v46
	v_mul_f32_e32 v42, v42, v47
	v_add_f32_e32 v32, 1.0, v32
	v_rcp_f32_e32 v43, v32
	v_mul_f32_e32 v32, v37, v156
	v_mul_f32_e32 v33, v33, v156
	v_mul_f32_e32 v40, v40, v43
	v_mul_f32_e32 v37, 0xbfb8aa3b, v32
	v_exp_f32_e32 v37, v37
	v_mul_f32_e32 v41, v32, v33
	v_add_f32_e32 v32, 1.0, v37
	v_rcp_f32_e32 v37, v32
	v_mul_f32_e32 v32, v38, v156
	v_mul_f32_e32 v33, v34, v156
	v_mul_f32_e32 v37, v41, v37
	v_mul_f32_e32 v34, 0xbfb8aa3b, v32
	v_exp_f32_e32 v38, v34
	v_mul_f32_e32 v34, v39, v156
	v_mul_f32_e32 v35, v35, v156
	v_mul_f32_e32 v32, v32, v33
	v_mul_f32_e32 v39, 0xbfb8aa3b, v34
	v_exp_f32_e32 v39, v39
	v_add_f32_e32 v38, 1.0, v38
	v_rcp_f32_e32 v38, v38
	v_add_f32_e32 v39, 1.0, v39
	v_rcp_f32_e32 v39, v39
	v_mul_f32_e32 v38, v32, v38
	v_mul_f32_e32 v32, v34, v35
	v_mul_f32_e32 v35, v32, v39
	v_cvt_pk_bf16_f32 v32, v44, v45
	v_cvt_pk_bf16_f32 v33, v36, v42
	v_cvt_pk_bf16_f32 v34, v40, v37
	v_cvt_pk_bf16_f32 v35, v38, v35
	v_mul_f32_e32 v38, v28, v152
	v_mul_f32_e32 v39, v24, v152
	v_mad_i64_i32 v[36:37], s[42:43], v150, s53, v[112:113]
	v_mul_f32_e32 v24, 0xbfb8aa3b, v38
	v_exp_f32_e32 v28, v24
	v_mul_f32_e32 v24, v29, v152
	v_mul_f32_e32 v25, v25, v152
	v_lshl_add_u64 v[36:37], v[36:37], 0, v[114:115]
	v_mul_f32_e32 v29, 0xbfb8aa3b, v24
	v_exp_f32_e32 v29, v29
	v_mul_f32_e32 v24, v24, v25
	v_mov_b32_e32 v25, v26
	v_add_f32_e32 v28, 1.0, v28
	v_add_f32_e32 v29, 1.0, v29
	v_rcp_f32_e32 v29, v29
	v_rcp_f32_e32 v28, v28
	global_store_dwordx4 v[36:37], v[32:35], off
	v_mul_f32_e32 v29, v24, v29
	v_mul_f32_e32 v24, v30, v152
	v_mul_f32_e32 v25, v25, v152
	v_mul_f32_e32 v32, v38, v39
	v_mul_f32_e32 v26, 0xbfb8aa3b, v24
	v_exp_f32_e32 v30, v26
	v_mul_f32_e32 v26, v31, v152
	v_mul_f32_e32 v27, v27, v152
	v_mul_f32_e32 v28, v32, v28
	v_mul_f32_e32 v31, 0xbfb8aa3b, v26
	v_exp_f32_e32 v31, v31
	v_mul_f32_e32 v32, v24, v25
	v_add_f32_e32 v24, 1.0, v30
	v_rcp_f32_e32 v30, v24
	v_add_f32_e32 v24, 1.0, v31
	v_rcp_f32_e32 v31, v24
	v_mul_f32_e32 v24, v20, v152
	v_mul_f32_e32 v25, v16, v152
	v_mul_f32_e32 v26, v26, v27
	v_mul_f32_e32 v16, 0xbfb8aa3b, v24
	v_exp_f32_e32 v16, v16
	v_mul_f32_e32 v24, v24, v25
	v_mul_f32_e32 v20, v32, v30
	v_mul_f32_e32 v26, v26, v31
	v_add_f32_e32 v16, 1.0, v16
	v_rcp_f32_e32 v27, v16
	v_mul_f32_e32 v16, v21, v152
	v_mul_f32_e32 v17, v17, v152
	v_mul_f32_e32 v24, v24, v27
	v_mul_f32_e32 v21, 0xbfb8aa3b, v16
	v_exp_f32_e32 v21, v21
	v_mul_f32_e32 v25, v16, v17
	v_add_f32_e32 v16, 1.0, v21
	v_rcp_f32_e32 v21, v16
	v_mul_f32_e32 v16, v22, v152
	v_mul_f32_e32 v17, v18, v152
	v_mul_f32_e32 v21, v25, v21
	v_mul_f32_e32 v18, 0xbfb8aa3b, v16
	v_exp_f32_e32 v22, v18
	v_mul_f32_e32 v18, v23, v152
	v_mul_f32_e32 v19, v19, v152
	v_mul_f32_e32 v16, v16, v17
	v_mul_f32_e32 v23, 0xbfb8aa3b, v18
	v_exp_f32_e32 v23, v23
	v_add_f32_e32 v22, 1.0, v22
	v_rcp_f32_e32 v22, v22
	v_add_f32_e32 v23, 1.0, v23
	v_rcp_f32_e32 v23, v23
	v_mul_f32_e32 v22, v16, v22
	v_mul_f32_e32 v16, v18, v19
	v_mul_f32_e32 v19, v16, v23
	v_cvt_pk_bf16_f32 v16, v28, v29
	v_cvt_pk_bf16_f32 v17, v20, v26
	v_cvt_pk_bf16_f32 v18, v24, v21
	v_cvt_pk_bf16_f32 v19, v22, v19
	v_mul_f32_e32 v22, v12, v148
	v_mul_f32_e32 v23, v8, v148
	v_mad_i64_i32 v[20:21], s[42:43], v146, s53, v[112:113]
	v_mul_f32_e32 v8, 0xbfb8aa3b, v22
	v_exp_f32_e32 v12, v8
	v_mul_f32_e32 v8, v13, v148
	v_mul_f32_e32 v9, v9, v148
	v_lshl_add_u64 v[20:21], v[20:21], 0, v[114:115]
	v_mul_f32_e32 v13, 0xbfb8aa3b, v8
	v_exp_f32_e32 v13, v13
	v_mul_f32_e32 v8, v8, v9
	v_mov_b32_e32 v9, v10
	v_add_f32_e32 v12, 1.0, v12
	v_add_f32_e32 v13, 1.0, v13
	v_rcp_f32_e32 v13, v13
	v_rcp_f32_e32 v12, v12
	global_store_dwordx4 v[20:21], v[16:19], off
	v_mul_f32_e32 v13, v8, v13
	v_mul_f32_e32 v8, v14, v148
	v_mul_f32_e32 v9, v9, v148
	v_mul_f32_e32 v16, v22, v23
	v_mul_f32_e32 v10, 0xbfb8aa3b, v8
	v_exp_f32_e32 v14, v10
	v_mul_f32_e32 v10, v15, v148
	v_mul_f32_e32 v11, v11, v148
	v_mul_f32_e32 v12, v16, v12
	v_mul_f32_e32 v15, 0xbfb8aa3b, v10
	v_exp_f32_e32 v15, v15
	v_mul_f32_e32 v16, v8, v9
	v_add_f32_e32 v8, 1.0, v14
	v_rcp_f32_e32 v14, v8
	v_add_f32_e32 v8, 1.0, v15
	v_rcp_f32_e32 v15, v8
	v_mul_f32_e32 v8, v4, v148
	v_mul_f32_e32 v9, v0, v148
	v_mul_f32_e32 v10, v10, v11
	v_mul_f32_e32 v0, 0xbfb8aa3b, v8
	v_exp_f32_e32 v0, v0
	v_mul_f32_e32 v8, v8, v9
	v_mul_f32_e32 v4, v16, v14
	v_mul_f32_e32 v10, v10, v15
	v_add_f32_e32 v0, 1.0, v0
	v_rcp_f32_e32 v11, v0
	v_mul_f32_e32 v0, v5, v148
	v_mul_f32_e32 v1, v1, v148
	v_mul_f32_e32 v8, v8, v11
	v_mul_f32_e32 v5, 0xbfb8aa3b, v0
	v_exp_f32_e32 v5, v5
	v_mul_f32_e32 v9, v0, v1
	v_add_f32_e32 v0, 1.0, v5
	v_rcp_f32_e32 v5, v0
	v_mul_f32_e32 v0, v6, v148
	v_mul_f32_e32 v1, v2, v148
	v_mul_f32_e32 v5, v9, v5
	v_mul_f32_e32 v2, 0xbfb8aa3b, v0
	v_exp_f32_e32 v6, v2
	v_mul_f32_e32 v2, v7, v148
	v_mul_f32_e32 v3, v3, v148
	v_mul_f32_e32 v0, v0, v1
	v_mul_f32_e32 v7, 0xbfb8aa3b, v2
	v_exp_f32_e32 v7, v7
	v_add_f32_e32 v6, 1.0, v6
	v_rcp_f32_e32 v6, v6
	v_add_f32_e32 v7, 1.0, v7
	v_rcp_f32_e32 v7, v7
	v_mul_f32_e32 v6, v0, v6
	v_mul_f32_e32 v0, v2, v3
	v_mul_f32_e32 v3, v0, v7
	v_cvt_pk_bf16_f32 v0, v12, v13
	v_cvt_pk_bf16_f32 v1, v4, v10
	v_cvt_pk_bf16_f32 v2, v8, v5
	v_mad_i64_i32 v[4:5], s[42:43], v144, s53, v[112:113]
	v_lshl_add_u64 v[4:5], v[4:5], 0, v[114:115]
	v_cvt_pk_bf16_f32 v3, v6, v3
	global_store_dwordx4 v[4:5], v[0:3], off
	s_cbranch_vccnz .LBB0_477
	s_andn2_b64 vcc, exec, s[4:5]
	s_cbranch_vccnz .LBB0_476
	s_barrier
	s_branch .LBB0_476

; __device__ __forceinline__ unsigned cvt_pk_bf16(float lo, float hi) { unsigned r; asm volatile("v_cvt_pk_bf16_f32 %0, %1, %2" : "=v"(r) : "v"(lo), "v"(hi)); return r; }
;     __device__ __forceinline__ void operator()(const f32x4 (&acc)[2][2][4][2], const Unit& u, int wr, int wc, int fr, int fq) const {
;     ...
;                 const int row = u.pm * BM + ai * HALF + wr * 64 + m * 16 + fr;
;                 const float rs = rsv[ai][m];
;                 bf16_t* rp = O + (size_t)row * 1536 + wc * 32 + 8 * fq;
;                 if (u.pn < 2) {
; #pragma unroll
;                     for (int bj = 0; bj < 2; ++bj) {
;                         const f32x4 v0 = acc[ai][bj][m][0] * rs, v1 = acc[ai][bj][m][1] * rs;
;                         u32x4 w; w.x = cvt_pk_bf16(v0[0], v0[1]); w.y = cvt_pk_bf16(v0[2], v0[3]); w.z = cvt_pk_bf16(v1[0], v1[1]); w.w = cvt_pk_bf16(v1[2], v1[3]);
;                         *(u32x4*)(rp + u.pn * BM + bj * HALF) = w;
;                     }
.LBB0_665:
	s_lshl_b32 s46, s4, 8
	s_andn2_b64 vcc, exec, s[50:51]
	s_ashr_i32 s47, s46, 31
	s_cbranch_vccnz .LBB0_667
	v_lshl_add_u64 v[162:163], s[46:47], 1, v[162:163]
	v_mul_f32_e32 v126, v126, v160
	v_mul_f32_e32 v127, v127, v160
	v_mul_f32_e32 v124, v124, v160
	v_mul_f32_e32 v125, v125, v160
	v_pk_mul_f32 v[178:179], v[122:123], v[160:161] op_sel_hi:[1,0]
	v_pk_mul_f32 v[122:123], v[120:121], v[160:161] op_sel_hi:[1,0]
	v_cvt_pk_bf16_f32 v120, v124, v125
	v_cvt_pk_bf16_f32 v121, v126, v127
	v_mul_f32_e32 v118, v118, v160
	v_mul_f32_e32 v119, v119, v160
	v_cvt_pk_bf16_f32 v122, v122, v123
	v_cvt_pk_bf16_f32 v123, v178, v179
	global_store_dwordx4 v[162:163], v[120:123], off
	v_mul_f32_e32 v116, v116, v160
	v_mul_f32_e32 v117, v117, v160
	s_nop 0
	v_pk_mul_f32 v[120:121], v[114:115], v[160:161] op_sel_hi:[1,0]
	v_pk_mul_f32 v[114:115], v[112:113], v[160:161] op_sel_hi:[1,0]
	v_cvt_pk_bf16_f32 v112, v116, v117
	v_cvt_pk_bf16_f32 v113, v118, v119
	s_nop 0
	v_cvt_pk_bf16_f32 v114, v114, v115
	v_cvt_pk_bf16_f32 v115, v120, v121
	global_store_dwordx4 v[162:163], v[112:115], off offset:256

; __device__ __forceinline__ unsigned cvt_pk_bf16(float lo, float hi) { unsigned r; asm volatile("v_cvt_pk_bf16_f32 %0, %1, %2" : "=v"(r) : "v"(lo), "v"(hi)); return r; }
;     __device__ __forceinline__ void operator()(const f32x4 (&acc)[2][2][4][2], const Unit& u, int wr, int wc, int fr, int fq) const {
;     ...
;                 const int row = u.pm * BM + ai * HALF + wr * 64 + m * 16 + fr;
;                 const float rs = rsv[ai][m];
;                 bf16_t* rp = O + (size_t)row * 1536 + wc * 32 + 8 * fq;
;                 if (u.pn < 2) {
; #pragma unroll
;                     for (int bj = 0; bj < 2; ++bj) {
;                         const f32x4 v0 = acc[ai][bj][m][0] * rs, v1 = acc[ai][bj][m][1] * rs;
;                         u32x4 w; w.x = cvt_pk_bf16(v0[0], v0[1]); w.y = cvt_pk_bf16(v0[2], v0[3]); w.z = cvt_pk_bf16(v1[0], v1[1]); w.w = cvt_pk_bf16(v1[2], v1[3]);
;                         *(u32x4*)(rp + u.pn * BM + bj * HALF) = w;
;                     }
.LBB0_669:
	s_andn2_b64 vcc, exec, s[48:49]
	s_cbranch_vccnz .LBB0_671
	v_lshl_add_u64 v[114:115], s[46:47], 1, v[114:115]
	v_mul_f32_e32 v110, v110, v112
	v_mul_f32_e32 v111, v111, v112
	v_mul_f32_e32 v108, v108, v112
	v_mul_f32_e32 v109, v109, v112
	v_pk_mul_f32 v[116:117], v[106:107], v[112:113] op_sel_hi:[1,0]
	v_pk_mul_f32 v[106:107], v[104:105], v[112:113] op_sel_hi:[1,0]
	v_cvt_pk_bf16_f32 v104, v108, v109
	v_cvt_pk_bf16_f32 v105, v110, v111
	v_mul_f32_e32 v102, v102, v112
	v_mul_f32_e32 v103, v103, v112
	v_cvt_pk_bf16_f32 v106, v106, v107
	v_cvt_pk_bf16_f32 v107, v116, v117
	global_store_dwordx4 v[114:115], v[104:107], off
	v_mul_f32_e32 v100, v100, v112
	v_mul_f32_e32 v101, v101, v112
	s_nop 0
	v_pk_mul_f32 v[104:105], v[98:99], v[112:113] op_sel_hi:[1,0]
	v_pk_mul_f32 v[98:99], v[96:97], v[112:113] op_sel_hi:[1,0]
	v_cvt_pk_bf16_f32 v96, v100, v101
	v_cvt_pk_bf16_f32 v97, v102, v103
	s_nop 0
	v_cvt_pk_bf16_f32 v98, v98, v99
	v_cvt_pk_bf16_f32 v99, v104, v105
	global_store_dwordx4 v[114:115], v[96:99], off offset:256

; __device__ __forceinline__ unsigned cvt_pk_bf16(float lo, float hi) { unsigned r; asm volatile("v_cvt_pk_bf16_f32 %0, %1, %2" : "=v"(r) : "v"(lo), "v"(hi)); return r; }
;     __device__ __forceinline__ void operator()(const f32x4 (&acc)[2][2][4][2], const Unit& u, int wr, int wc, int fr, int fq) const {
;     ...
;                 const int row = u.pm * BM + ai * HALF + wr * 64 + m * 16 + fr;
;                 const float rs = rsv[ai][m];
;                 bf16_t* rp = O + (size_t)row * 1536 + wc * 32 + 8 * fq;
;                 if (u.pn < 2) {
; #pragma unroll
;                     for (int bj = 0; bj < 2; ++bj) {
;                         const f32x4 v0 = acc[ai][bj][m][0] * rs, v1 = acc[ai][bj][m][1] * rs;
;                         u32x4 w; w.x = cvt_pk_bf16(v0[0], v0[1]); w.y = cvt_pk_bf16(v0[2], v0[3]); w.z = cvt_pk_bf16(v1[0], v1[1]); w.w = cvt_pk_bf16(v1[2], v1[3]);
;                         *(u32x4*)(rp + u.pn * BM + bj * HALF) = w;
;                     }
.LBB0_673:
	s_andn2_b64 vcc, exec, s[48:49]
	s_cbranch_vccnz .LBB0_675
	v_lshl_add_u64 v[98:99], s[46:47], 1, v[98:99]
	v_mul_f32_e32 v94, v94, v96
	v_mul_f32_e32 v95, v95, v96
	v_mul_f32_e32 v92, v92, v96
	v_mul_f32_e32 v93, v93, v96
	v_pk_mul_f32 v[100:101], v[90:91], v[96:97] op_sel_hi:[1,0]
	v_pk_mul_f32 v[90:91], v[88:89], v[96:97] op_sel_hi:[1,0]
	v_cvt_pk_bf16_f32 v88, v92, v93
	v_cvt_pk_bf16_f32 v89, v94, v95
	v_mul_f32_e32 v86, v86, v96
	v_mul_f32_e32 v87, v87, v96
	v_cvt_pk_bf16_f32 v90, v90, v91
	v_cvt_pk_bf16_f32 v91, v100, v101
	global_store_dwordx4 v[98:99], v[88:91], off
	v_mul_f32_e32 v84, v84, v96
	v_mul_f32_e32 v85, v85, v96
	s_nop 0
	v_pk_mul_f32 v[88:89], v[82:83], v[96:97] op_sel_hi:[1,0]
	v_pk_mul_f32 v[82:83], v[80:81], v[96:97] op_sel_hi:[1,0]
	v_cvt_pk_bf16_f32 v80, v84, v85
	v_cvt_pk_bf16_f32 v81, v86, v87
	s_nop 0
	v_cvt_pk_bf16_f32 v82, v82, v83
	v_cvt_pk_bf16_f32 v83, v88, v89
	global_store_dwordx4 v[98:99], v[80:83], off offset:256

; __device__ __forceinline__ unsigned cvt_pk_bf16(float lo, float hi) { unsigned r; asm volatile("v_cvt_pk_bf16_f32 %0, %1, %2" : "=v"(r) : "v"(lo), "v"(hi)); return r; }
;     __device__ __forceinline__ void operator()(const f32x4 (&acc)[2][2][4][2], const Unit& u, int wr, int wc, int fr, int fq) const {
;     ...
;                 const int row = u.pm * BM + ai * HALF + wr * 64 + m * 16 + fr;
;                 const float rs = rsv[ai][m];
;                 bf16_t* rp = O + (size_t)row * 1536 + wc * 32 + 8 * fq;
;                 if (u.pn < 2) {
; #pragma unroll
;                     for (int bj = 0; bj < 2; ++bj) {
;                         const f32x4 v0 = acc[ai][bj][m][0] * rs, v1 = acc[ai][bj][m][1] * rs;
;                         u32x4 w; w.x = cvt_pk_bf16(v0[0], v0[1]); w.y = cvt_pk_bf16(v0[2], v0[3]); w.z = cvt_pk_bf16(v1[0], v1[1]); w.w = cvt_pk_bf16(v1[2], v1[3]);
;                         *(u32x4*)(rp + u.pn * BM + bj * HALF) = w;
;                     }
.LBB0_677:
	s_andn2_b64 vcc, exec, s[48:49]
	s_cbranch_vccnz .LBB0_679
	v_lshl_add_u64 v[82:83], s[46:47], 1, v[82:83]
	v_mul_f32_e32 v78, v78, v80
	v_mul_f32_e32 v79, v79, v80
	v_mul_f32_e32 v76, v76, v80
	v_mul_f32_e32 v77, v77, v80
	v_pk_mul_f32 v[84:85], v[74:75], v[80:81] op_sel_hi:[1,0]
	v_pk_mul_f32 v[74:75], v[72:73], v[80:81] op_sel_hi:[1,0]
	v_cvt_pk_bf16_f32 v72, v76, v77
	v_cvt_pk_bf16_f32 v73, v78, v79
	v_mul_f32_e32 v70, v70, v80
	v_mul_f32_e32 v71, v71, v80
	v_cvt_pk_bf16_f32 v74, v74, v75
	v_cvt_pk_bf16_f32 v75, v84, v85
	global_store_dwordx4 v[82:83], v[72:75], off
	v_mul_f32_e32 v68, v68, v80
	v_mul_f32_e32 v69, v69, v80
	s_nop 0
	v_pk_mul_f32 v[72:73], v[66:67], v[80:81] op_sel_hi:[1,0]
	v_pk_mul_f32 v[66:67], v[64:65], v[80:81] op_sel_hi:[1,0]
	v_cvt_pk_bf16_f32 v64, v68, v69
	v_cvt_pk_bf16_f32 v65, v70, v71
	s_nop 0
	v_cvt_pk_bf16_f32 v66, v66, v67
	v_cvt_pk_bf16_f32 v67, v72, v73
	global_store_dwordx4 v[82:83], v[64:67], off offset:256

; __device__ __forceinline__ unsigned cvt_pk_bf16(float lo, float hi) { unsigned r; asm volatile("v_cvt_pk_bf16_f32 %0, %1, %2" : "=v"(r) : "v"(lo), "v"(hi)); return r; }
;     __device__ __forceinline__ void operator()(const f32x4 (&acc)[2][2][4][2], const Unit& u, int wr, int wc, int fr, int fq) const {
;     ...
;                 const int row = u.pm * BM + ai * HALF + wr * 64 + m * 16 + fr;
;                 const float rs = rsv[ai][m];
;                 bf16_t* rp = O + (size_t)row * 1536 + wc * 32 + 8 * fq;
;                 if (u.pn < 2) {
; #pragma unroll
;                     for (int bj = 0; bj < 2; ++bj) {
;                         const f32x4 v0 = acc[ai][bj][m][0] * rs, v1 = acc[ai][bj][m][1] * rs;
;                         u32x4 w; w.x = cvt_pk_bf16(v0[0], v0[1]); w.y = cvt_pk_bf16(v0[2], v0[3]); w.z = cvt_pk_bf16(v1[0], v1[1]); w.w = cvt_pk_bf16(v1[2], v1[3]);
;                         *(u32x4*)(rp + u.pn * BM + bj * HALF) = w;
;                     }
.LBB0_681:
	s_andn2_b64 vcc, exec, s[48:49]
	s_cbranch_vccnz .LBB0_683
	v_lshl_add_u64 v[66:67], s[46:47], 1, v[66:67]
	v_mul_f32_e32 v62, v62, v64
	v_mul_f32_e32 v63, v63, v64
	v_mul_f32_e32 v60, v60, v64
	v_mul_f32_e32 v61, v61, v64
	v_pk_mul_f32 v[68:69], v[58:59], v[64:65] op_sel_hi:[1,0]
	v_pk_mul_f32 v[58:59], v[56:57], v[64:65] op_sel_hi:[1,0]
	v_cvt_pk_bf16_f32 v56, v60, v61
	v_cvt_pk_bf16_f32 v57, v62, v63
	v_mul_f32_e32 v54, v54, v64
	v_mul_f32_e32 v55, v55, v64
	v_cvt_pk_bf16_f32 v58, v58, v59
	v_cvt_pk_bf16_f32 v59, v68, v69
	global_store_dwordx4 v[66:67], v[56:59], off
	v_mul_f32_e32 v52, v52, v64
	v_mul_f32_e32 v53, v53, v64
	s_nop 0
	v_pk_mul_f32 v[56:57], v[50:51], v[64:65] op_sel_hi:[1,0]
	v_pk_mul_f32 v[50:51], v[48:49], v[64:65] op_sel_hi:[1,0]
	v_cvt_pk_bf16_f32 v48, v52, v53
	v_cvt_pk_bf16_f32 v49, v54, v55
	s_nop 0
	v_cvt_pk_bf16_f32 v50, v50, v51
	v_cvt_pk_bf16_f32 v51, v56, v57
	global_store_dwordx4 v[66:67], v[48:51], off offset:256

; __device__ __forceinline__ unsigned cvt_pk_bf16(float lo, float hi) { unsigned r; asm volatile("v_cvt_pk_bf16_f32 %0, %1, %2" : "=v"(r) : "v"(lo), "v"(hi)); return r; }
;     __device__ __forceinline__ void operator()(const f32x4 (&acc)[2][2][4][2], const Unit& u, int wr, int wc, int fr, int fq) const {
;     ...
;                 const int row = u.pm * BM + ai * HALF + wr * 64 + m * 16 + fr;
;                 const float rs = rsv[ai][m];
;                 bf16_t* rp = O + (size_t)row * 1536 + wc * 32 + 8 * fq;
;                 if (u.pn < 2) {
; #pragma unroll
;                     for (int bj = 0; bj < 2; ++bj) {
;                         const f32x4 v0 = acc[ai][bj][m][0] * rs, v1 = acc[ai][bj][m][1] * rs;
;                         u32x4 w; w.x = cvt_pk_bf16(v0[0], v0[1]); w.y = cvt_pk_bf16(v0[2], v0[3]); w.z = cvt_pk_bf16(v1[0], v1[1]); w.w = cvt_pk_bf16(v1[2], v1[3]);
;                         *(u32x4*)(rp + u.pn * BM + bj * HALF) = w;
;                     }
.LBB0_685:
	s_andn2_b64 vcc, exec, s[48:49]
	s_cbranch_vccnz .LBB0_687
	v_lshl_add_u64 v[50:51], s[46:47], 1, v[50:51]
	v_mul_f32_e32 v46, v46, v48
	v_mul_f32_e32 v47, v47, v48
	v_mul_f32_e32 v44, v44, v48
	v_mul_f32_e32 v45, v45, v48
	v_pk_mul_f32 v[52:53], v[42:43], v[48:49] op_sel_hi:[1,0]
	v_pk_mul_f32 v[42:43], v[40:41], v[48:49] op_sel_hi:[1,0]
	v_cvt_pk_bf16_f32 v40, v44, v45
	v_cvt_pk_bf16_f32 v41, v46, v47
	v_mul_f32_e32 v38, v38, v48
	v_mul_f32_e32 v39, v39, v48
	v_cvt_pk_bf16_f32 v42, v42, v43
	v_cvt_pk_bf16_f32 v43, v52, v53
	global_store_dwordx4 v[50:51], v[40:43], off
	v_mul_f32_e32 v36, v36, v48
	v_mul_f32_e32 v37, v37, v48
	s_nop 0
	v_pk_mul_f32 v[40:41], v[34:35], v[48:49] op_sel_hi:[1,0]
	v_pk_mul_f32 v[34:35], v[32:33], v[48:49] op_sel_hi:[1,0]
	v_cvt_pk_bf16_f32 v32, v36, v37
	v_cvt_pk_bf16_f32 v33, v38, v39
	s_nop 0
	v_cvt_pk_bf16_f32 v34, v34, v35
	v_cvt_pk_bf16_f32 v35, v40, v41
	global_store_dwordx4 v[50:51], v[32:35], off offset:256

; __device__ __forceinline__ unsigned cvt_pk_bf16(float lo, float hi) { unsigned r; asm volatile("v_cvt_pk_bf16_f32 %0, %1, %2" : "=v"(r) : "v"(lo), "v"(hi)); return r; }
;     __device__ __forceinline__ void operator()(const f32x4 (&acc)[2][2][4][2], const Unit& u, int wr, int wc, int fr, int fq) const {
;     ...
;                 const int row = u.pm * BM + ai * HALF + wr * 64 + m * 16 + fr;
;                 const float rs = rsv[ai][m];
;                 bf16_t* rp = O + (size_t)row * 1536 + wc * 32 + 8 * fq;
;                 if (u.pn < 2) {
; #pragma unroll
;                     for (int bj = 0; bj < 2; ++bj) {
;                         const f32x4 v0 = acc[ai][bj][m][0] * rs, v1 = acc[ai][bj][m][1] * rs;
;                         u32x4 w; w.x = cvt_pk_bf16(v0[0], v0[1]); w.y = cvt_pk_bf16(v0[2], v0[3]); w.z = cvt_pk_bf16(v1[0], v1[1]); w.w = cvt_pk_bf16(v1[2], v1[3]);
;                         *(u32x4*)(rp + u.pn * BM + bj * HALF) = w;
;                     }
.LBB0_689:
	s_andn2_b64 vcc, exec, s[48:49]
	s_cbranch_vccnz .LBB0_691
	v_lshl_add_u64 v[34:35], s[46:47], 1, v[34:35]
	v_mul_f32_e32 v30, v30, v32
	v_mul_f32_e32 v31, v31, v32
	v_mul_f32_e32 v28, v28, v32
	v_mul_f32_e32 v29, v29, v32
	v_pk_mul_f32 v[36:37], v[26:27], v[32:33] op_sel_hi:[1,0]
	v_pk_mul_f32 v[26:27], v[24:25], v[32:33] op_sel_hi:[1,0]
	v_cvt_pk_bf16_f32 v24, v28, v29
	v_cvt_pk_bf16_f32 v25, v30, v31
	v_mul_f32_e32 v22, v22, v32
	v_mul_f32_e32 v23, v23, v32
	v_cvt_pk_bf16_f32 v26, v26, v27
	v_cvt_pk_bf16_f32 v27, v36, v37
	global_store_dwordx4 v[34:35], v[24:27], off
	v_mul_f32_e32 v20, v20, v32
	v_mul_f32_e32 v21, v21, v32
	s_nop 0
	v_pk_mul_f32 v[24:25], v[18:19], v[32:33] op_sel_hi:[1,0]
	v_pk_mul_f32 v[18:19], v[16:17], v[32:33] op_sel_hi:[1,0]
	v_cvt_pk_bf16_f32 v16, v20, v21
	v_cvt_pk_bf16_f32 v17, v22, v23
	s_nop 0
	v_cvt_pk_bf16_f32 v18, v18, v19
	v_cvt_pk_bf16_f32 v19, v24, v25
	global_store_dwordx4 v[34:35], v[16:19], off offset:256

; __device__ __forceinline__ unsigned cvt_pk_bf16(float lo, float hi) { unsigned r; asm volatile("v_cvt_pk_bf16_f32 %0, %1, %2" : "=v"(r) : "v"(lo), "v"(hi)); return r; }
;     __device__ __forceinline__ void operator()(const f32x4 (&acc)[2][2][4][2], const Unit& u, int wr, int wc, int fr, int fq) const {
;     ...
;                 const int row = u.pm * BM + ai * HALF + wr * 64 + m * 16 + fr;
;                 const float rs = rsv[ai][m];
;                 bf16_t* rp = O + (size_t)row * 1536 + wc * 32 + 8 * fq;
;                 if (u.pn < 2) {
; #pragma unroll
;                     for (int bj = 0; bj < 2; ++bj) {
;                         const f32x4 v0 = acc[ai][bj][m][0] * rs, v1 = acc[ai][bj][m][1] * rs;
;                         u32x4 w; w.x = cvt_pk_bf16(v0[0], v0[1]); w.y = cvt_pk_bf16(v0[2], v0[3]); w.z = cvt_pk_bf16(v1[0], v1[1]); w.w = cvt_pk_bf16(v1[2], v1[3]);
;                         *(u32x4*)(rp + u.pn * BM + bj * HALF) = w;
;                     }
.LBB0_695:
	v_lshl_add_u64 v[18:19], s[46:47], 1, v[18:19]
	v_mul_f32_e32 v14, v14, v16
	v_mul_f32_e32 v15, v15, v16
	v_mul_f32_e32 v12, v12, v16
	v_mul_f32_e32 v13, v13, v16
	v_pk_mul_f32 v[20:21], v[10:11], v[16:17] op_sel_hi:[1,0]
	v_pk_mul_f32 v[10:11], v[8:9], v[16:17] op_sel_hi:[1,0]
	v_cvt_pk_bf16_f32 v8, v12, v13
	v_cvt_pk_bf16_f32 v9, v14, v15
	v_mul_f32_e32 v6, v6, v16
	v_mul_f32_e32 v7, v7, v16
	v_cvt_pk_bf16_f32 v10, v10, v11
	v_cvt_pk_bf16_f32 v11, v20, v21
	global_store_dwordx4 v[18:19], v[8:11], off
	v_mul_f32_e32 v4, v4, v16
	v_mul_f32_e32 v5, v5, v16
	s_nop 0
	v_pk_mul_f32 v[8:9], v[2:3], v[16:17] op_sel_hi:[1,0]
	v_pk_mul_f32 v[2:3], v[0:1], v[16:17] op_sel_hi:[1,0]
	v_cvt_pk_bf16_f32 v0, v4, v5
	v_cvt_pk_bf16_f32 v1, v6, v7
	s_nop 0
	v_cvt_pk_bf16_f32 v2, v2, v3
	v_cvt_pk_bf16_f32 v3, v8, v9
	global_store_dwordx4 v[18:19], v[0:3], off offset:256
	s_andn2_b64 vcc, exec, s[38:39]
	s_mov_b64 s[0:1], -1
	s_cbranch_vccnz .LBB0_655

; __device__ __forceinline__ float fast_sigmoid(float x) { return __builtin_amdgcn_rcpf(1.0f + __expf(-x)); }
; __device__ __forceinline__ void rows_rstd(const float* ssq, int row0, int fq, float (&rs)[2][4]) {
;     f32x4 pr[2][4];
; #pragma unroll
;     for (int ai = 0; ai < 2; ++ai)
; #pragma unroll
;         for (int m = 0; m < 4; ++m) pr[ai][m] = *(const f32x4*)(ssq + (size_t)(row0 + ai * HALF + m * 16) * 16 + 4 * fq);
; #pragma unroll
;     for (int ai = 0; ai < 2; ++ai)
; #pragma unroll
;         for (int m = 0; m < 4; ++m) { float t = (pr[ai][m][0] + pr[ai][m][1]) + (pr[ai][m][2] + pr[ai][m][3]); t += __shfl_xor(t, 16); t += __shfl_xor(t, 32); rs[ai][m] = __builtin_amdgcn_rsqf(t * (1.0f / 1024.0f) + 1e-6f); }
;     __device__ __forceinline__ void operator()(const f32x4 (&acc)[2][2][4][2], const Unit& u, int wr, int wc, int fr, int fq) const {
;     ...
;                 const int row = u.pm * BM + ai * HALF + wr * 64 + m * 16 + fr;
;                 const float rs = rsv[ai][m];
;                 float h[8];
; #pragma unroll
;                 for (int n = 0; n < 2; ++n)
; #pragma unroll
;                     for (int i = 0; i < 4; ++i) { const float g = acc[ai][0][m][n][i] * rs, up = acc[ai][1][m][n][i] * rs; h[4 * n + i] = g * up * fast_sigmoid(g); }
.LBB0_980:
	v_mbcnt_lo_u32_b32 v252, -1, 0
	v_mbcnt_hi_u32_b32 v252, -1, v252
	v_and_b32_e32 v252, 48, v252
	v_lshl_add_u32 v252, v149, 6, v252
	v_add_u32_e32 v252, 0x20000, v252
	v_lshl_add_u32 v170, s30, 8, v149
	v_ashrrev_i32_e32 v171, 31, v170
	v_or_b32_e32 v166, 16, v170
	v_lshlrev_b64 v[144:145], 6, v[170:171]
	v_ashrrev_i32_e32 v167, 31, v166
	v_or_b32_e32 v162, 32, v170
	v_lshl_add_u64 v[144:145], v[136:137], 0, v[144:145]
	v_lshlrev_b64 v[146:147], 6, v[166:167]
	v_ashrrev_i32_e32 v163, 31, v162
	v_or_b32_e32 v158, 48, v170
	v_lshl_add_u64 v[146:147], v[136:137], 0, v[146:147]
	ds_read_b128 v[178:181], v252 offset:0
	ds_read_b128 v[182:185], v252 offset:1024
	v_lshlrev_b64 v[144:145], 6, v[162:163]
	v_ashrrev_i32_e32 v159, 31, v158
	v_add_u32_e32 v154, 0x80, v170
	v_lshl_add_u64 v[144:145], v[136:137], 0, v[144:145]
	v_lshlrev_b64 v[146:147], 6, v[158:159]
	v_ashrrev_i32_e32 v155, 31, v154
	v_lshl_add_u64 v[146:147], v[136:137], 0, v[146:147]
	ds_read_b128 v[186:189], v252 offset:2048
	ds_read_b128 v[190:193], v252 offset:3072
	v_lshlrev_b64 v[144:145], 6, v[154:155]
	v_lshl_add_u64 v[144:145], v[136:137], 0, v[144:145]
	ds_read_b128 v[194:197], v252 offset:8192
	v_add_u32_e32 v150, 0x90, v170
	v_ashrrev_i32_e32 v151, 31, v150
	v_lshlrev_b64 v[144:145], 6, v[150:151]
	v_add_u32_e32 v146, 0xa0, v170
	v_lshl_add_u64 v[144:145], v[136:137], 0, v[144:145]
	v_ashrrev_i32_e32 v147, 31, v146
	ds_read_b128 v[198:201], v252 offset:9216
	v_lshlrev_b64 v[144:145], 6, v[146:147]
	v_lshl_add_u64 v[144:145], v[136:137], 0, v[144:145]
	ds_read_b128 v[202:205], v252 offset:10240
	v_add_u32_e32 v144, 0xb0, v170
	v_ashrrev_i32_e32 v145, 31, v144
	v_lshlrev_b64 v[206:207], 6, v[144:145]
	v_lshl_add_u64 v[206:207], v[136:137], 0, v[206:207]
	ds_read_b128 v[206:209], v252 offset:11264
	v_and_b32_e32 v147, 64, v175
	v_xor_b32_e32 v145, 16, v175
	v_add_u32_e32 v147, 64, v147
	v_xor_b32_e32 v148, 32, v175
	v_cmp_lt_i32_e32 vcc, v145, v147
	v_lshl_or_b32 v172, s28, 7, v157
	v_ashrrev_i32_e32 v173, 31, v172
	v_cndmask_b32_e32 v145, v175, v145, vcc
	v_cmp_lt_i32_e32 vcc, v148, v147
	v_lshlrev_b32_e32 v145, 2, v145
	s_waitcnt lgkmcnt(0)
	v_mov_b32_e32 v210, v179
	v_mov_b32_e32 v211, v180
	v_mov_b32_e32 v179, v181
	v_pk_add_f32 v[178:179], v[210:211], v[178:179]
	v_mov_b32_e32 v180, v183
	v_mov_b32_e32 v181, v184
	v_mov_b32_e32 v183, v185
	v_cndmask_b32_e32 v147, v175, v148, vcc
	v_mov_b32_e32 v184, v187
	v_mov_b32_e32 v185, v188
	v_mov_b32_e32 v187, v189
	v_mov_b32_e32 v188, v191
	v_mov_b32_e32 v189, v192
	v_mov_b32_e32 v191, v193
	v_add_f32_e32 v148, v178, v179
	v_pk_add_f32 v[178:179], v[180:181], v[182:183]
	v_pk_add_f32 v[180:181], v[184:185], v[186:187]
	v_pk_add_f32 v[182:183], v[188:189], v[190:191]
	v_mov_b32_e32 v192, v195
	v_mov_b32_e32 v193, v196
	v_mov_b32_e32 v195, v197
	ds_bpermute_b32 v151, v145, v148
	v_add_f32_e32 v152, v178, v179
	v_add_f32_e32 v155, v180, v181
	v_add_f32_e32 v156, v182, v183
	v_pk_add_f32 v[184:185], v[192:193], v[194:195]
	ds_bpermute_b32 v160, v145, v152
	ds_bpermute_b32 v163, v145, v155
	ds_bpermute_b32 v164, v145, v156
	v_add_f32_e32 v159, v184, v185
	ds_bpermute_b32 v167, v145, v159
	v_lshlrev_b32_e32 v147, 2, v147
	s_waitcnt lgkmcnt(4)
	v_add_f32_e32 v148, v148, v151
	ds_bpermute_b32 v151, v147, v148
	s_waitcnt lgkmcnt(4)
	v_add_f32_e32 v152, v152, v160
	s_waitcnt lgkmcnt(3)
	v_add_f32_e32 v155, v155, v163
	s_waitcnt lgkmcnt(2)
	v_add_f32_e32 v156, v156, v164
	ds_bpermute_b32 v160, v147, v152
	ds_bpermute_b32 v163, v147, v155
	ds_bpermute_b32 v164, v147, v156
	s_waitcnt lgkmcnt(4)
	v_add_f32_e32 v159, v159, v167
	ds_bpermute_b32 v167, v147, v159
	s_waitcnt lgkmcnt(4)
	v_add_f32_e32 v148, v148, v151
	v_fmamk_f32 v148, v148, 0x3a800000, v176
	s_waitcnt lgkmcnt(3)
	v_add_f32_e32 v151, v152, v160
	s_waitcnt lgkmcnt(2)
	v_add_f32_e32 v152, v155, v163
	s_waitcnt lgkmcnt(1)
	v_add_f32_e32 v155, v156, v164
	v_mov_b32_e32 v180, v199
	v_mov_b32_e32 v181, v200
	v_mov_b32_e32 v199, v201
	v_rsq_f32_e32 v178, v148
	v_fmamk_f32 v148, v151, 0x3a800000, v176
	v_fmamk_f32 v151, v152, 0x3a800000, v176
	v_fmamk_f32 v152, v155, 0x3a800000, v176
	v_pk_add_f32 v[180:181], v[180:181], v[198:199]
	v_rsq_f32_e32 v174, v148
	v_add_f32_e32 v148, v180, v181
	v_rsq_f32_e32 v164, v152
	s_waitcnt lgkmcnt(0)
	v_add_f32_e32 v152, v159, v167
	v_mov_b32_e32 v180, v203
	v_mov_b32_e32 v181, v204
	v_mov_b32_e32 v203, v205
	v_fmamk_f32 v152, v152, 0x3a800000, v176
	v_pk_add_f32 v[180:181], v[180:181], v[202:203]
	v_rsq_f32_e32 v160, v152
	v_add_f32_e32 v152, v180, v181
	v_mov_b32_e32 v180, v207
	v_mov_b32_e32 v181, v208
	v_mov_b32_e32 v207, v209
	v_pk_add_f32 v[180:181], v[180:181], v[206:207]
	v_rsq_f32_e32 v168, v151
	v_add_f32_e32 v156, v180, v181
	v_mul_f32_e32 v180, v124, v178
	v_mul_f32_e32 v181, v120, v178
	ds_bpermute_b32 v151, v145, v148
	v_mul_f32_e32 v120, 0xbfb8aa3b, v180
	v_exp_f32_e32 v124, v120
	v_mul_f32_e32 v120, v125, v178
	v_mul_f32_e32 v121, v121, v178
	s_waitcnt lgkmcnt(0)
	v_add_f32_e32 v148, v148, v151
	v_mul_f32_e32 v125, 0xbfb8aa3b, v120
	v_exp_f32_e32 v125, v125
	ds_bpermute_b32 v151, v147, v148
	ds_bpermute_b32 v155, v145, v152
	ds_bpermute_b32 v145, v145, v156
	v_add_f32_e32 v125, 1.0, v125
	v_rcp_f32_e32 v125, v125
	v_mul_f32_e32 v120, v120, v121
	s_waitcnt lgkmcnt(2)
	v_add_f32_e32 v148, v148, v151
	s_waitcnt lgkmcnt(1)
	v_add_f32_e32 v151, v152, v155
	s_waitcnt lgkmcnt(0)
; __device__ __forceinline__ unsigned cvt_pk_bf16(float lo, float hi) { unsigned r; asm volatile("v_cvt_pk_bf16_f32 %0, %1, %2" : "=v"(r) : "v"(lo), "v"(hi)); return r; }
; __device__ __forceinline__ float fast_sigmoid(float x) { return __builtin_amdgcn_rcpf(1.0f + __expf(-x)); }
;     __device__ __forceinline__ void operator()(const f32x4 (&acc)[2][2][4][2], const Unit& u, int wr, int wc, int fr, int fq) const {
;     ...
;         for (int ai = 0; ai < 2; ++ai)
; #pragma unroll
;             for (int m = 0; m < 4; ++m) {
;                 const int row = u.pm * BM + ai * HALF + wr * 64 + m * 16 + fr;
;                 const float rs = rsv[ai][m];
;                 float h[8];
; #pragma unroll
;                 for (int n = 0; n < 2; ++n)
; #pragma unroll
;                     for (int i = 0; i < 4; ++i) { const float g = acc[ai][0][m][n][i] * rs, up = acc[ai][1][m][n][i] * rs; h[4 * n + i] = g * up * fast_sigmoid(g); }
;                 u32x4 w; w.x = cvt_pk_bf16(h[0], h[1]); w.y = cvt_pk_bf16(h[2], h[3]); w.z = cvt_pk_bf16(h[4], h[5]); w.w = cvt_pk_bf16(h[6], h[7]);
;                 *(u32x4*)(H + (size_t)row * 2816 + col0) = w;
	v_add_f32_e32 v145, v156, v145
	v_mul_f32_e32 v125, v120, v125
	ds_bpermute_b32 v152, v147, v151
	ds_bpermute_b32 v147, v147, v145
	v_mul_f32_e32 v120, v126, v178
	v_mul_f32_e32 v121, v122, v178
	v_add_f32_e32 v124, 1.0, v124
	v_mul_f32_e32 v122, 0xbfb8aa3b, v120
	v_exp_f32_e32 v126, v122
	v_mul_f32_e32 v122, v127, v178
	v_mul_f32_e32 v123, v123, v178
	v_fmamk_f32 v148, v148, 0x3a800000, v176
	v_rcp_f32_e32 v124, v124
	v_mul_f32_e32 v127, 0xbfb8aa3b, v122
	v_rsq_f32_e32 v156, v148
	s_waitcnt lgkmcnt(1)
	v_add_f32_e32 v148, v151, v152
	s_waitcnt lgkmcnt(0)
	v_add_f32_e32 v145, v145, v147
	v_exp_f32_e32 v127, v127
	v_fmamk_f32 v148, v148, 0x3a800000, v176
	v_fmamk_f32 v145, v145, 0x3a800000, v176
	v_rsq_f32_e32 v152, v148
	v_rsq_f32_e32 v148, v145
	v_mul_f32_e32 v145, v180, v181
	v_mul_f32_e32 v124, v145, v124
	v_mul_f32_e32 v145, v120, v121
	v_add_f32_e32 v120, 1.0, v126
	v_rcp_f32_e32 v126, v120
	v_add_f32_e32 v120, 1.0, v127
	v_rcp_f32_e32 v127, v120
	v_mul_f32_e32 v120, v116, v178
	v_mul_f32_e32 v121, v112, v178
	v_mul_f32_e32 v116, v122, v123
	v_mul_f32_e32 v112, 0xbfb8aa3b, v120
	v_exp_f32_e32 v112, v112
	v_mul_f32_e32 v122, v116, v127
	v_mul_f32_e32 v120, v120, v121
	v_mul_f32_e32 v126, v145, v126
	v_add_f32_e32 v112, 1.0, v112
	v_rcp_f32_e32 v116, v112
	v_mul_f32_e32 v112, v117, v178
	v_mul_f32_e32 v113, v113, v178
	v_mov_b32_e32 v123, v104
	v_mul_f32_e32 v117, 0xbfb8aa3b, v112
	v_exp_f32_e32 v117, v117
	v_mul_f32_e32 v120, v120, v116
	v_mul_f32_e32 v116, v112, v113
	v_add_f32_e32 v112, 1.0, v117
	v_rcp_f32_e32 v117, v112
	v_mul_f32_e32 v112, v118, v178
	v_mul_f32_e32 v113, v114, v178
	s_andn2_b64 vcc, exec, s[22:23]
	v_mul_f32_e32 v114, 0xbfb8aa3b, v112
	v_exp_f32_e32 v118, v114
	v_mul_f32_e32 v114, v119, v178
	v_mul_f32_e32 v115, v115, v178
	v_mul_f32_e32 v121, v116, v117
	v_mul_f32_e32 v119, 0xbfb8aa3b, v114
	v_exp_f32_e32 v119, v119
	v_add_f32_e32 v116, 1.0, v118
	v_rcp_f32_e32 v116, v116
	v_mul_f32_e32 v112, v112, v113
	v_add_f32_e32 v117, 1.0, v119
	v_rcp_f32_e32 v117, v117
	v_mul_f32_e32 v113, v114, v115
	v_mul_f32_e32 v112, v112, v116
	v_cvt_pk_bf16_f32 v116, v124, v125
	v_mul_f32_e32 v113, v113, v117
	v_cvt_pk_bf16_f32 v117, v126, v122
	v_mul_f32_e32 v122, v108, v174
	v_mul_f32_e32 v123, v123, v174
	v_cvt_pk_bf16_f32 v118, v120, v121
	v_cvt_pk_bf16_f32 v119, v112, v113
	v_mov_b64_e32 v[112:113], s[6:7]
	v_mul_f32_e32 v104, 0xbfb8aa3b, v122
	v_exp_f32_e32 v108, v104
	v_mul_f32_e32 v104, v109, v174
	v_mul_f32_e32 v105, v105, v174
	v_mad_i64_i32 v[120:121], s[34:35], v170, s52, v[112:113]
	v_mul_f32_e32 v109, 0xbfb8aa3b, v104
	v_exp_f32_e32 v109, v109
	v_mul_f32_e32 v104, v104, v105
	v_mov_b32_e32 v105, v106
	v_add_f32_e32 v108, 1.0, v108
	v_add_f32_e32 v109, 1.0, v109
	v_rcp_f32_e32 v109, v109
	v_rcp_f32_e32 v108, v108
	v_lshlrev_b64 v[114:115], 1, v[172:173]
	v_lshl_add_u64 v[120:121], v[120:121], 0, v[114:115]
	v_mul_f32_e32 v109, v104, v109
	v_mul_f32_e32 v104, v110, v174
	v_mul_f32_e32 v105, v105, v174
	global_store_dwordx4 v[120:121], v[116:119], off
	v_mul_f32_e32 v106, 0xbfb8aa3b, v104
	v_exp_f32_e32 v110, v106
	v_mul_f32_e32 v106, v111, v174
	v_mul_f32_e32 v107, v107, v174
	v_mul_f32_e32 v116, v122, v123
	v_mul_f32_e32 v111, 0xbfb8aa3b, v106
	v_exp_f32_e32 v111, v111
	v_mul_f32_e32 v108, v116, v108
	v_mul_f32_e32 v116, v104, v105
	v_add_f32_e32 v104, 1.0, v110
	v_rcp_f32_e32 v110, v104
	v_add_f32_e32 v104, 1.0, v111
	v_rcp_f32_e32 v111, v104
	v_mul_f32_e32 v104, v100, v174
	v_mul_f32_e32 v105, v96, v174
	v_mul_f32_e32 v106, v106, v107
	v_mul_f32_e32 v96, 0xbfb8aa3b, v104
	v_exp_f32_e32 v96, v96
	v_mul_f32_e32 v104, v104, v105
	v_mul_f32_e32 v100, v116, v110
	v_mul_f32_e32 v106, v106, v111
	v_add_f32_e32 v96, 1.0, v96
	v_rcp_f32_e32 v107, v96
	v_mul_f32_e32 v96, v101, v174
	v_mul_f32_e32 v97, v97, v174
	s_mov_b64 s[22:23], -1
	v_mul_f32_e32 v101, 0xbfb8aa3b, v96
	v_exp_f32_e32 v101, v101
	v_mul_f32_e32 v105, v96, v97
	v_mov_b32_e32 v97, v98
	v_mul_f32_e32 v104, v104, v107
	v_add_f32_e32 v96, 1.0, v101
	v_rcp_f32_e32 v101, v96
	v_mul_f32_e32 v96, v102, v174
	v_mul_f32_e32 v97, v97, v174
	v_mul_f32_e32 v101, v105, v101
	v_mul_f32_e32 v98, 0xbfb8aa3b, v96
	v_exp_f32_e32 v102, v98
	v_mul_f32_e32 v98, v103, v174
	v_mul_f32_e32 v99, v99, v174
	v_mul_f32_e32 v96, v96, v97
	v_mul_f32_e32 v103, 0xbfb8aa3b, v98
	v_exp_f32_e32 v103, v103
	v_add_f32_e32 v102, 1.0, v102
	v_rcp_f32_e32 v102, v102
	v_add_f32_e32 v103, 1.0, v103
	v_rcp_f32_e32 v103, v103
	v_mul_f32_e32 v102, v96, v102
	v_mul_f32_e32 v96, v98, v99
	v_mul_f32_e32 v99, v96, v103
	v_cvt_pk_bf16_f32 v96, v108, v109
	v_cvt_pk_bf16_f32 v97, v100, v106
	v_cvt_pk_bf16_f32 v98, v104, v101
	v_cvt_pk_bf16_f32 v99, v102, v99
	v_mul_f32_e32 v102, v92, v168
	v_mul_f32_e32 v103, v88, v168
	v_mad_i64_i32 v[100:101], s[34:35], v166, s52, v[112:113]
	v_mul_f32_e32 v88, 0xbfb8aa3b, v102
	v_exp_f32_e32 v92, v88
	v_mul_f32_e32 v88, v93, v168
	v_mul_f32_e32 v89, v89, v168
	v_lshl_add_u64 v[100:101], v[100:101], 0, v[114:115]
	v_mul_f32_e32 v93, 0xbfb8aa3b, v88
	v_exp_f32_e32 v93, v93
	v_mul_f32_e32 v88, v88, v89
	v_mov_b32_e32 v89, v90
	v_add_f32_e32 v92, 1.0, v92
	v_add_f32_e32 v93, 1.0, v93
	v_rcp_f32_e32 v93, v93
	v_rcp_f32_e32 v92, v92
	global_store_dwordx4 v[100:101], v[96:99], off
	v_mul_f32_e32 v93, v88, v93
	v_mul_f32_e32 v88, v94, v168
	v_mul_f32_e32 v89, v89, v168
	v_mul_f32_e32 v96, v102, v103
	v_mul_f32_e32 v90, 0xbfb8aa3b, v88
	v_exp_f32_e32 v94, v90
	v_mul_f32_e32 v90, v95, v168
	v_mul_f32_e32 v91, v91, v168
	v_mul_f32_e32 v92, v96, v92
	v_mul_f32_e32 v95, 0xbfb8aa3b, v90
	v_exp_f32_e32 v95, v95
	v_mul_f32_e32 v96, v88, v89
	v_add_f32_e32 v88, 1.0, v94
	v_rcp_f32_e32 v94, v88
; __device__ __forceinline__ unsigned cvt_pk_bf16(float lo, float hi) { unsigned r; asm volatile("v_cvt_pk_bf16_f32 %0, %1, %2" : "=v"(r) : "v"(lo), "v"(hi)); return r; }
; __device__ __forceinline__ float fast_sigmoid(float x) { return __builtin_amdgcn_rcpf(1.0f + __expf(-x)); }
;     __device__ __forceinline__ void operator()(const f32x4 (&acc)[2][2][4][2], const Unit& u, int wr, int wc, int fr, int fq) const {
;     ...
;         for (int ai = 0; ai < 2; ++ai)
; #pragma unroll
;             for (int m = 0; m < 4; ++m) {
;                 const int row = u.pm * BM + ai * HALF + wr * 64 + m * 16 + fr;
;                 const float rs = rsv[ai][m];
;                 float h[8];
; #pragma unroll
;                 for (int n = 0; n < 2; ++n)
; #pragma unroll
;                     for (int i = 0; i < 4; ++i) { const float g = acc[ai][0][m][n][i] * rs, up = acc[ai][1][m][n][i] * rs; h[4 * n + i] = g * up * fast_sigmoid(g); }
;                 u32x4 w; w.x = cvt_pk_bf16(h[0], h[1]); w.y = cvt_pk_bf16(h[2], h[3]); w.z = cvt_pk_bf16(h[4], h[5]); w.w = cvt_pk_bf16(h[6], h[7]);
;                 *(u32x4*)(H + (size_t)row * 2816 + col0) = w;
	v_add_f32_e32 v88, 1.0, v95
	v_rcp_f32_e32 v95, v88
	v_mul_f32_e32 v88, v84, v168
	v_mul_f32_e32 v89, v80, v168
	v_mul_f32_e32 v90, v90, v91
	v_mul_f32_e32 v80, 0xbfb8aa3b, v88
	v_exp_f32_e32 v80, v80
	v_mul_f32_e32 v88, v88, v89
	v_mul_f32_e32 v84, v96, v94
	v_mul_f32_e32 v90, v90, v95
	v_add_f32_e32 v80, 1.0, v80
	v_rcp_f32_e32 v91, v80
	v_mul_f32_e32 v80, v85, v168
	v_mul_f32_e32 v81, v81, v168
	v_mul_f32_e32 v88, v88, v91
	v_mul_f32_e32 v85, 0xbfb8aa3b, v80
	v_exp_f32_e32 v85, v85
	v_mul_f32_e32 v89, v80, v81
	v_add_f32_e32 v80, 1.0, v85
	v_rcp_f32_e32 v85, v80
	v_mul_f32_e32 v80, v86, v168
	v_mul_f32_e32 v81, v82, v168
	v_mul_f32_e32 v85, v89, v85
	v_mul_f32_e32 v82, 0xbfb8aa3b, v80
	v_exp_f32_e32 v86, v82
	v_mul_f32_e32 v82, v87, v168
	v_mul_f32_e32 v83, v83, v168
	v_mul_f32_e32 v80, v80, v81
	v_mul_f32_e32 v87, 0xbfb8aa3b, v82
	v_exp_f32_e32 v87, v87
	v_add_f32_e32 v86, 1.0, v86
	v_rcp_f32_e32 v86, v86
	v_add_f32_e32 v87, 1.0, v87
	v_rcp_f32_e32 v87, v87
	v_mul_f32_e32 v86, v80, v86
	v_mul_f32_e32 v80, v82, v83
	v_mul_f32_e32 v83, v80, v87
	v_cvt_pk_bf16_f32 v80, v92, v93
	v_cvt_pk_bf16_f32 v81, v84, v90
	v_cvt_pk_bf16_f32 v82, v88, v85
	v_cvt_pk_bf16_f32 v83, v86, v83
	v_mul_f32_e32 v86, v76, v164
	v_mul_f32_e32 v87, v72, v164
	v_mad_i64_i32 v[84:85], s[34:35], v162, s52, v[112:113]
	v_mul_f32_e32 v72, 0xbfb8aa3b, v86
	v_exp_f32_e32 v76, v72
	v_mul_f32_e32 v72, v77, v164
	v_mul_f32_e32 v73, v73, v164
	v_lshl_add_u64 v[84:85], v[84:85], 0, v[114:115]
	v_mul_f32_e32 v77, 0xbfb8aa3b, v72
	v_exp_f32_e32 v77, v77
	v_mul_f32_e32 v72, v72, v73
	v_mov_b32_e32 v73, v74
	v_add_f32_e32 v76, 1.0, v76
	v_add_f32_e32 v77, 1.0, v77
	v_rcp_f32_e32 v77, v77
	v_rcp_f32_e32 v76, v76
	global_store_dwordx4 v[84:85], v[80:83], off
	v_mul_f32_e32 v77, v72, v77
	v_mul_f32_e32 v72, v78, v164
	v_mul_f32_e32 v73, v73, v164
	v_mul_f32_e32 v80, v86, v87
	v_mul_f32_e32 v74, 0xbfb8aa3b, v72
	v_exp_f32_e32 v78, v74
	v_mul_f32_e32 v74, v79, v164
	v_mul_f32_e32 v75, v75, v164
	v_mul_f32_e32 v76, v80, v76
	v_mul_f32_e32 v79, 0xbfb8aa3b, v74
	v_exp_f32_e32 v79, v79
	v_mul_f32_e32 v80, v72, v73
	v_add_f32_e32 v72, 1.0, v78
	v_rcp_f32_e32 v78, v72
	v_add_f32_e32 v72, 1.0, v79
	v_rcp_f32_e32 v79, v72
	v_mul_f32_e32 v72, v68, v164
	v_mul_f32_e32 v73, v64, v164
	v_mul_f32_e32 v74, v74, v75
	v_mul_f32_e32 v64, 0xbfb8aa3b, v72
	v_exp_f32_e32 v64, v64
	v_mul_f32_e32 v72, v72, v73
	v_mul_f32_e32 v68, v80, v78
	v_mul_f32_e32 v74, v74, v79
	v_add_f32_e32 v64, 1.0, v64
	v_rcp_f32_e32 v75, v64
	v_mul_f32_e32 v64, v69, v164
	v_mul_f32_e32 v65, v65, v164
	v_mul_f32_e32 v72, v72, v75
	v_mul_f32_e32 v69, 0xbfb8aa3b, v64
	v_exp_f32_e32 v69, v69
	v_mul_f32_e32 v73, v64, v65
	v_add_f32_e32 v64, 1.0, v69
	v_rcp_f32_e32 v69, v64
	v_mul_f32_e32 v64, v70, v164
	v_mul_f32_e32 v65, v66, v164
	v_mul_f32_e32 v69, v73, v69
	v_mul_f32_e32 v66, 0xbfb8aa3b, v64
	v_exp_f32_e32 v70, v66
	v_mul_f32_e32 v66, v71, v164
	v_mul_f32_e32 v67, v67, v164
	v_mul_f32_e32 v64, v64, v65
	v_mul_f32_e32 v71, 0xbfb8aa3b, v66
	v_exp_f32_e32 v71, v71
	v_add_f32_e32 v70, 1.0, v70
	v_rcp_f32_e32 v70, v70
	v_add_f32_e32 v71, 1.0, v71
	v_rcp_f32_e32 v71, v71
	v_mul_f32_e32 v70, v64, v70
	v_mul_f32_e32 v64, v66, v67
	v_mul_f32_e32 v67, v64, v71
	v_cvt_pk_bf16_f32 v64, v76, v77
	v_cvt_pk_bf16_f32 v65, v68, v74
	v_cvt_pk_bf16_f32 v66, v72, v69
	v_cvt_pk_bf16_f32 v67, v70, v67
	v_mul_f32_e32 v70, v60, v160
	v_mul_f32_e32 v71, v56, v160
	v_mad_i64_i32 v[68:69], s[34:35], v158, s52, v[112:113]
	v_mul_f32_e32 v56, 0xbfb8aa3b, v70
	v_exp_f32_e32 v60, v56
	v_mul_f32_e32 v56, v61, v160
	v_mul_f32_e32 v57, v57, v160
	v_lshl_add_u64 v[68:69], v[68:69], 0, v[114:115]
	v_mul_f32_e32 v61, 0xbfb8aa3b, v56
	v_exp_f32_e32 v61, v61
	v_mul_f32_e32 v56, v56, v57
	v_mov_b32_e32 v57, v58
	v_add_f32_e32 v60, 1.0, v60
	v_add_f32_e32 v61, 1.0, v61
	v_rcp_f32_e32 v61, v61
	v_rcp_f32_e32 v60, v60
	global_store_dwordx4 v[68:69], v[64:67], off
	v_mul_f32_e32 v61, v56, v61
	v_mul_f32_e32 v56, v62, v160
	v_mul_f32_e32 v57, v57, v160
	v_mul_f32_e32 v64, v70, v71
	v_mul_f32_e32 v58, 0xbfb8aa3b, v56
	v_exp_f32_e32 v62, v58
	v_mul_f32_e32 v58, v63, v160
	v_mul_f32_e32 v59, v59, v160
	v_mul_f32_e32 v60, v64, v60
	v_mul_f32_e32 v63, 0xbfb8aa3b, v58
	v_exp_f32_e32 v63, v63
	v_mul_f32_e32 v64, v56, v57
	v_add_f32_e32 v56, 1.0, v62
	v_rcp_f32_e32 v62, v56
	v_add_f32_e32 v56, 1.0, v63
	v_rcp_f32_e32 v63, v56
	v_mul_f32_e32 v56, v52, v160
	v_mul_f32_e32 v57, v48, v160
	v_mul_f32_e32 v58, v58, v59
	v_mul_f32_e32 v48, 0xbfb8aa3b, v56
	v_exp_f32_e32 v48, v48
	v_mul_f32_e32 v56, v56, v57
	v_mul_f32_e32 v52, v64, v62
	v_mul_f32_e32 v58, v58, v63
	v_add_f32_e32 v48, 1.0, v48
	v_rcp_f32_e32 v59, v48
	v_mul_f32_e32 v48, v53, v160
	v_mul_f32_e32 v49, v49, v160
	v_mul_f32_e32 v56, v56, v59
	v_mul_f32_e32 v53, 0xbfb8aa3b, v48
	v_exp_f32_e32 v53, v53
	v_mul_f32_e32 v57, v48, v49
	v_add_f32_e32 v48, 1.0, v53
	v_rcp_f32_e32 v53, v48
	v_mul_f32_e32 v48, v54, v160
	v_mul_f32_e32 v49, v50, v160
	v_mul_f32_e32 v53, v57, v53
	v_mul_f32_e32 v50, 0xbfb8aa3b, v48
	v_exp_f32_e32 v54, v50
	v_mul_f32_e32 v50, v55, v160
	v_mul_f32_e32 v51, v51, v160
	v_mul_f32_e32 v48, v48, v49
	v_mul_f32_e32 v55, 0xbfb8aa3b, v50
	v_exp_f32_e32 v55, v55
	v_add_f32_e32 v54, 1.0, v54
	v_rcp_f32_e32 v54, v54
	v_add_f32_e32 v55, 1.0, v55
	v_rcp_f32_e32 v55, v55
	v_mul_f32_e32 v54, v48, v54
	v_mul_f32_e32 v48, v50, v51
	v_mul_f32_e32 v51, v48, v55
	v_cvt_pk_bf16_f32 v48, v60, v61
	v_cvt_pk_bf16_f32 v49, v52, v58
	v_cvt_pk_bf16_f32 v50, v56, v53
	v_cvt_pk_bf16_f32 v51, v54, v51
	v_mul_f32_e32 v54, v44, v156
	v_mul_f32_e32 v55, v40, v156
	v_mad_i64_i32 v[52:53], s[34:35], v154, s52, v[112:113]
; __device__ __forceinline__ unsigned cvt_pk_bf16(float lo, float hi) { unsigned r; asm volatile("v_cvt_pk_bf16_f32 %0, %1, %2" : "=v"(r) : "v"(lo), "v"(hi)); return r; }
; __device__ __forceinline__ float fast_sigmoid(float x) { return __builtin_amdgcn_rcpf(1.0f + __expf(-x)); }
;     __device__ __forceinline__ void operator()(const f32x4 (&acc)[2][2][4][2], const Unit& u, int wr, int wc, int fr, int fq) const {
;     ...
;         for (int ai = 0; ai < 2; ++ai)
; #pragma unroll
;             for (int m = 0; m < 4; ++m) {
;                 const int row = u.pm * BM + ai * HALF + wr * 64 + m * 16 + fr;
;                 const float rs = rsv[ai][m];
;                 float h[8];
; #pragma unroll
;                 for (int n = 0; n < 2; ++n)
; #pragma unroll
;                     for (int i = 0; i < 4; ++i) { const float g = acc[ai][0][m][n][i] * rs, up = acc[ai][1][m][n][i] * rs; h[4 * n + i] = g * up * fast_sigmoid(g); }
;                 u32x4 w; w.x = cvt_pk_bf16(h[0], h[1]); w.y = cvt_pk_bf16(h[2], h[3]); w.z = cvt_pk_bf16(h[4], h[5]); w.w = cvt_pk_bf16(h[6], h[7]);
;                 *(u32x4*)(H + (size_t)row * 2816 + col0) = w;
	v_mul_f32_e32 v40, 0xbfb8aa3b, v54
	v_exp_f32_e32 v44, v40
	v_mul_f32_e32 v40, v45, v156
	v_mul_f32_e32 v41, v41, v156
	v_lshl_add_u64 v[52:53], v[52:53], 0, v[114:115]
	v_mul_f32_e32 v45, 0xbfb8aa3b, v40
	v_exp_f32_e32 v45, v45
	v_mul_f32_e32 v40, v40, v41
	v_mov_b32_e32 v41, v42
	v_add_f32_e32 v44, 1.0, v44
	v_add_f32_e32 v45, 1.0, v45
	v_rcp_f32_e32 v45, v45
	v_rcp_f32_e32 v44, v44
	global_store_dwordx4 v[52:53], v[48:51], off
	v_mul_f32_e32 v45, v40, v45
	v_mul_f32_e32 v40, v46, v156
	v_mul_f32_e32 v41, v41, v156
	v_mul_f32_e32 v48, v54, v55
	v_mul_f32_e32 v42, 0xbfb8aa3b, v40
	v_exp_f32_e32 v46, v42
	v_mul_f32_e32 v42, v47, v156
	v_mul_f32_e32 v43, v43, v156
	v_mul_f32_e32 v44, v48, v44
	v_mul_f32_e32 v47, 0xbfb8aa3b, v42
	v_exp_f32_e32 v47, v47
	v_mul_f32_e32 v48, v40, v41
	v_add_f32_e32 v40, 1.0, v46
	v_rcp_f32_e32 v46, v40
	v_add_f32_e32 v40, 1.0, v47
	v_rcp_f32_e32 v47, v40
	v_mul_f32_e32 v40, v36, v156
	v_mul_f32_e32 v41, v32, v156
	v_mul_f32_e32 v42, v42, v43
	v_mul_f32_e32 v32, 0xbfb8aa3b, v40
	v_exp_f32_e32 v32, v32
	v_mul_f32_e32 v40, v40, v41
	v_mul_f32_e32 v36, v48, v46
	v_mul_f32_e32 v42, v42, v47
	v_add_f32_e32 v32, 1.0, v32
	v_rcp_f32_e32 v43, v32
	v_mul_f32_e32 v32, v37, v156
	v_mul_f32_e32 v33, v33, v156
	v_mul_f32_e32 v40, v40, v43
	v_mul_f32_e32 v37, 0xbfb8aa3b, v32
	v_exp_f32_e32 v37, v37
	v_mul_f32_e32 v41, v32, v33
	v_add_f32_e32 v32, 1.0, v37
	v_rcp_f32_e32 v37, v32
	v_mul_f32_e32 v32, v38, v156
	v_mul_f32_e32 v33, v34, v156
	v_mul_f32_e32 v37, v41, v37
	v_mul_f32_e32 v34, 0xbfb8aa3b, v32
	v_exp_f32_e32 v38, v34
	v_mul_f32_e32 v34, v39, v156
	v_mul_f32_e32 v35, v35, v156
	v_mul_f32_e32 v32, v32, v33
	v_mul_f32_e32 v39, 0xbfb8aa3b, v34
	v_exp_f32_e32 v39, v39
	v_add_f32_e32 v38, 1.0, v38
	v_rcp_f32_e32 v38, v38
	v_add_f32_e32 v39, 1.0, v39
	v_rcp_f32_e32 v39, v39
	v_mul_f32_e32 v38, v32, v38
	v_mul_f32_e32 v32, v34, v35
	v_mul_f32_e32 v35, v32, v39
	v_cvt_pk_bf16_f32 v32, v44, v45
	v_cvt_pk_bf16_f32 v33, v36, v42
	v_cvt_pk_bf16_f32 v34, v40, v37
	v_cvt_pk_bf16_f32 v35, v38, v35
	v_mul_f32_e32 v38, v28, v152
	v_mul_f32_e32 v39, v24, v152
	v_mad_i64_i32 v[36:37], s[34:35], v150, s52, v[112:113]
	v_mul_f32_e32 v24, 0xbfb8aa3b, v38
	v_exp_f32_e32 v28, v24
	v_mul_f32_e32 v24, v29, v152
	v_mul_f32_e32 v25, v25, v152
	v_lshl_add_u64 v[36:37], v[36:37], 0, v[114:115]
	v_mul_f32_e32 v29, 0xbfb8aa3b, v24
	v_exp_f32_e32 v29, v29
	v_mul_f32_e32 v24, v24, v25
	v_mov_b32_e32 v25, v26
	v_add_f32_e32 v28, 1.0, v28
	v_add_f32_e32 v29, 1.0, v29
	v_rcp_f32_e32 v29, v29
	v_rcp_f32_e32 v28, v28
	global_store_dwordx4 v[36:37], v[32:35], off
	v_mul_f32_e32 v29, v24, v29
	v_mul_f32_e32 v24, v30, v152
	v_mul_f32_e32 v25, v25, v152
	v_mul_f32_e32 v32, v38, v39
	v_mul_f32_e32 v26, 0xbfb8aa3b, v24
	v_exp_f32_e32 v30, v26
	v_mul_f32_e32 v26, v31, v152
	v_mul_f32_e32 v27, v27, v152
	v_mul_f32_e32 v28, v32, v28
	v_mul_f32_e32 v31, 0xbfb8aa3b, v26
	v_exp_f32_e32 v31, v31
	v_mul_f32_e32 v32, v24, v25
	v_add_f32_e32 v24, 1.0, v30
	v_rcp_f32_e32 v30, v24
	v_add_f32_e32 v24, 1.0, v31
	v_rcp_f32_e32 v31, v24
	v_mul_f32_e32 v24, v20, v152
	v_mul_f32_e32 v25, v16, v152
	v_mul_f32_e32 v26, v26, v27
	v_mul_f32_e32 v16, 0xbfb8aa3b, v24
	v_exp_f32_e32 v16, v16
	v_mul_f32_e32 v24, v24, v25
	v_mul_f32_e32 v20, v32, v30
	v_mul_f32_e32 v26, v26, v31
	v_add_f32_e32 v16, 1.0, v16
	v_rcp_f32_e32 v27, v16
	v_mul_f32_e32 v16, v21, v152
	v_mul_f32_e32 v17, v17, v152
	v_mul_f32_e32 v24, v24, v27
	v_mul_f32_e32 v21, 0xbfb8aa3b, v16
	v_exp_f32_e32 v21, v21
	v_mul_f32_e32 v25, v16, v17
	v_add_f32_e32 v16, 1.0, v21
	v_rcp_f32_e32 v21, v16
	v_mul_f32_e32 v16, v22, v152
	v_mul_f32_e32 v17, v18, v152
	v_mul_f32_e32 v21, v25, v21
	v_mul_f32_e32 v18, 0xbfb8aa3b, v16
	v_exp_f32_e32 v22, v18
	v_mul_f32_e32 v18, v23, v152
	v_mul_f32_e32 v19, v19, v152
	v_mul_f32_e32 v16, v16, v17
	v_mul_f32_e32 v23, 0xbfb8aa3b, v18
	v_exp_f32_e32 v23, v23
	v_add_f32_e32 v22, 1.0, v22
	v_rcp_f32_e32 v22, v22
	v_add_f32_e32 v23, 1.0, v23
	v_rcp_f32_e32 v23, v23
	v_mul_f32_e32 v22, v16, v22
	v_mul_f32_e32 v16, v18, v19
	v_mul_f32_e32 v19, v16, v23
	v_cvt_pk_bf16_f32 v16, v28, v29
	v_cvt_pk_bf16_f32 v17, v20, v26
	v_cvt_pk_bf16_f32 v18, v24, v21
	v_cvt_pk_bf16_f32 v19, v22, v19
	v_mul_f32_e32 v22, v12, v148
	v_mul_f32_e32 v23, v8, v148
	v_mad_i64_i32 v[20:21], s[34:35], v146, s52, v[112:113]
	v_mul_f32_e32 v8, 0xbfb8aa3b, v22
	v_exp_f32_e32 v12, v8
	v_mul_f32_e32 v8, v13, v148
	v_mul_f32_e32 v9, v9, v148
	v_lshl_add_u64 v[20:21], v[20:21], 0, v[114:115]
	v_mul_f32_e32 v13, 0xbfb8aa3b, v8
	v_exp_f32_e32 v13, v13
	v_mul_f32_e32 v8, v8, v9
	v_mov_b32_e32 v9, v10
	v_add_f32_e32 v12, 1.0, v12
	v_add_f32_e32 v13, 1.0, v13
	v_rcp_f32_e32 v13, v13
	v_rcp_f32_e32 v12, v12
	global_store_dwordx4 v[20:21], v[16:19], off
	v_mul_f32_e32 v13, v8, v13
	v_mul_f32_e32 v8, v14, v148
	v_mul_f32_e32 v9, v9, v148
	v_mul_f32_e32 v16, v22, v23
	v_mul_f32_e32 v10, 0xbfb8aa3b, v8
	v_exp_f32_e32 v14, v10
	v_mul_f32_e32 v10, v15, v148
	v_mul_f32_e32 v11, v11, v148
	v_mul_f32_e32 v12, v16, v12
	v_mul_f32_e32 v15, 0xbfb8aa3b, v10
	v_exp_f32_e32 v15, v15
	v_mul_f32_e32 v16, v8, v9
	v_add_f32_e32 v8, 1.0, v14
	v_rcp_f32_e32 v14, v8
	v_add_f32_e32 v8, 1.0, v15
	v_rcp_f32_e32 v15, v8
	v_mul_f32_e32 v8, v4, v148
	v_mul_f32_e32 v9, v0, v148
	v_mul_f32_e32 v10, v10, v11
	v_mul_f32_e32 v0, 0xbfb8aa3b, v8
	v_exp_f32_e32 v0, v0
	v_mul_f32_e32 v8, v8, v9
	v_mul_f32_e32 v4, v16, v14
	v_mul_f32_e32 v10, v10, v15
	v_add_f32_e32 v0, 1.0, v0
	v_rcp_f32_e32 v11, v0
	v_mul_f32_e32 v0, v5, v148
	v_mul_f32_e32 v1, v1, v148
	v_mul_f32_e32 v8, v8, v11
	v_mul_f32_e32 v5, 0xbfb8aa3b, v0
	v_exp_f32_e32 v5, v5
	v_mul_f32_e32 v9, v0, v1
	v_add_f32_e32 v0, 1.0, v5
	v_rcp_f32_e32 v5, v0
	v_mul_f32_e32 v0, v6, v148
	v_mul_f32_e32 v1, v2, v148
	v_mul_f32_e32 v5, v9, v5
	v_mul_f32_e32 v2, 0xbfb8aa3b, v0
	v_exp_f32_e32 v6, v2
	v_mul_f32_e32 v2, v7, v148
	v_mul_f32_e32 v3, v3, v148
	v_mul_f32_e32 v0, v0, v1
	v_mul_f32_e32 v7, 0xbfb8aa3b, v2
	v_exp_f32_e32 v7, v7
	v_add_f32_e32 v6, 1.0, v6
	v_rcp_f32_e32 v6, v6
	v_add_f32_e32 v7, 1.0, v7
	v_rcp_f32_e32 v7, v7
	v_mul_f32_e32 v6, v0, v6
	v_mul_f32_e32 v0, v2, v3
	v_mul_f32_e32 v3, v0, v7
	v_cvt_pk_bf16_f32 v0, v12, v13
	v_cvt_pk_bf16_f32 v1, v4, v10
	v_cvt_pk_bf16_f32 v2, v8, v5
	v_mad_i64_i32 v[4:5], s[34:35], v144, s52, v[112:113]
	v_lshl_add_u64 v[4:5], v[4:5], 0, v[114:115]
	v_cvt_pk_bf16_f32 v3, v6, v3
	global_store_dwordx4 v[4:5], v[0:3], off
	s_cbranch_vccnz .LBB0_972
	s_andn2_b64 vcc, exec, s[8:9]
	s_cbranch_vccnz .LBB0_971
	s_barrier
	s_branch .LBB0_971
